# scan: pair-scaled recurrence (loader pre-scales adjacent step pairs by the decay, state rescaled once per 2 steps) + XCD-affine map
# baseline (speedup 1.0000x reference)
; #define LAS __attribute__((address_space(3)))
; __device__ __forceinline__ int opaque_tid() { int t = threadIdx.x; asm volatile("" : "+v"(t)); return t; }
; __device__ __forceinline__ void rwkv_scan(const Params& p, LAS unsigned char* lds, int rowbase, int T, int h, int q4, const float* S0, float* Sout) {
;     const int tid = opaque_tid(), lane = tid & 63, w = __builtin_amdgcn_readfirstlane(tid >> 6), rowl = lane >> 4, seg = lane & 15; const int vloc = (w & 3) * 4 + rowl, vrow = q4 * 16 + vloc;
;     unsigned char* ws = p.ws;
;     const float* decay = p.out; const bf16_t* kk = (const bf16_t*)((const unsigned char*)p.out + 68157440); const bf16_t* kka = (const bf16_t*)((const unsigned char*)p.out + 68157440 + HALF512);
;     const bf16_t* kp = (const bf16_t*)(ws + WS_PRW); const bf16_t* rb = (const bf16_t*)(ws + WS_A); const bf16_t* vb = (const bf16_t*)(ws + WS_A + HALF512);
;     bf16_t* ob = (bf16_t*)(ws + WS_B);
;     const bool comp = w < 4;
;     f32x4 S = (f32x4){0.f, 0.f, 0.f, 0.f};
;     if (comp && S0) S = *(const f32x4*)(S0 + vrow * 64 + seg * 4);
;     constexpr int BUF = 43008;
;     const bool ldr = w >= 4; const int lt = tid & 255, lstep = lt >> 4, lj = lt & 15;
;     f32x4 gd[2]; u32x2 gk[2], ga[2], gp[2], gr[2], gv[2];
;     auto gload = [&](int c) {
;         if (ldr) {
; #pragma unroll
;             for (int q = 0; q < 2; ++q) {
;                 const size_t row = (size_t)(rowbase + c * 32 + lstep + q * 16); const size_t o = row * 512 + h * 64 + lj * 4;
;                 gd[q] = *(const f32x4*)(decay + o); gk[q] = *(const u32x2*)(kk + o); ga[q] = *(const u32x2*)(kka + o); gp[q] = *(const u32x2*)(kp + o); gr[q] = *(const u32x2*)(rb + o);
;                 gv[q] = *(const u32x2*)(vb + row * 512 + h * 64 + q4 * 16 + (lj & 3) * 4);
;             }
;         }
;     };
; __device__ __forceinline__ void ph_scan(const Params& p, LAS unsigned char* lds) {
;     ...
;     for (int task = blockIdx.x; task < 768; task += gridDim.x) {
;         if (task < 256) { const int b = task >> 5, h = (task >> 2) & 7, q4 = task & 3; rwkv_scan(p, lds, b * 4096, 4096, h, q4, nullptr, p.out + O_PRW + (size_t)(b * 8 + h) * 4096); }
.LBB0_757:
	s_and_b32 s47, s44, 7
	s_lshr_b32 s5, s44, 3
	s_lshl_b32 s47, s47, 3
	s_lshr_b32 s4, s5, 2
	s_add_i32 s47, s47, s4
	s_lshl_b32 s47, s47, 2
	s_and_b32 s5, s5, 3
	s_or_b32 s47, s47, s5
	s_bfe_u32 s45, s47, 0x30002
	v_mov_b32_e32 v14, v200
	s_ashr_i32 s33, s47, 5
	v_readfirstlane_b32 s4, v14
	s_ashr_i32 s46, s4, 6
	s_lshl_b32 s4, s47, 4
	s_lshl_b32 s42, s33, 12
	s_and_b32 s43, s4, 48
	s_cmp_lt_i32 s46, 4
	s_cselect_b64 s[30:31], -1, 0
	s_cmp_gt_i32 s46, 3
	s_waitcnt vmcnt(0)
	v_and_b32_e32 v12, 15, v14
	s_cselect_b64 s[38:39], -1, 0
	v_bfe_u32 v13, v14, 4, 4
	v_lshlrev_b32_e32 v13, 1, v13
	s_and_b64 vcc, exec, s[38:39]
	v_lshlrev_b32_e32 v15, 2, v12
	s_cbranch_vccz .LBB0_759
	v_or_b32_e32 v8, s42, v13
	v_ashrrev_i32_e32 v9, 31, v8
	s_lshl_b32 s22, s45, 6
	v_lshlrev_b32_e32 v16, 2, v12
	v_lshlrev_b64 v[2:3], 9, v[8:9]
	v_or_b32_e32 v0, s22, v16
	v_or_b32_e32 v2, v2, v0
	v_lshl_add_u64 v[4:5], v[2:3], 2, s[90:91]
	v_lshlrev_b64 v[2:3], 1, v[2:3]
	v_lshl_add_u64 v[10:11], s[6:7], 0, v[2:3]
	global_load_dwordx4 v[4:7], v[4:5], off
	s_nop 0
	global_load_dwordx2 v[18:19], v[10:11], off
	v_lshl_add_u64 v[10:11], s[8:9], 0, v[2:3]
	global_load_dwordx2 v[20:21], v[10:11], off
	v_lshl_add_u64 v[10:11], s[10:11], 0, v[2:3]
	v_lshl_add_u64 v[24:25], s[12:13], 0, v[2:3]
	v_lshlrev_b64 v[2:3], 10, v[8:9]
	v_lshl_add_u64 v[2:3], s[16:17], 0, v[2:3]
	s_lshl_b32 s4, s45, 7
	s_mov_b32 s5, s23
	v_or_b32_e32 v34, 1, v8
	v_lshl_add_u64 v[2:3], v[2:3], 0, s[4:5]
	s_lshl_b32 s50, s43, 1
	s_mov_b32 s51, s23
	v_ashrrev_i32_e32 v35, 31, v34
	v_lshl_add_u64 v[22:23], v[2:3], 0, s[50:51]
	v_and_b32_e32 v2, 12, v16
	v_lshlrev_b64 v[8:9], 9, v[34:35]
	v_lshlrev_b64 v[34:35], 10, v[34:35]
	v_lshlrev_b32_e32 v28, 1, v2
	v_mov_b32_e32 v29, v1
	v_or_b32_e32 v8, v8, v0
	v_lshl_add_u64 v[34:35], s[16:17], 0, v[34:35]
	v_lshl_add_u64 v[26:27], v[22:23], 0, v[28:29]
	v_lshlrev_b64 v[36:37], 1, v[8:9]
	v_lshl_add_u64 v[34:35], v[34:35], 0, s[4:5]
	global_load_dwordx2 v[22:23], v[10:11], off
	s_nop 0
	global_load_dwordx2 v[24:25], v[24:25], off
	s_nop 0
	global_load_dwordx2 v[26:27], v[26:27], off
	v_lshl_add_u64 v[10:11], v[8:9], 2, s[90:91]
	v_lshl_add_u64 v[30:31], s[6:7], 0, v[36:37]
	v_lshl_add_u64 v[32:33], s[8:9], 0, v[36:37]
	v_lshl_add_u64 v[38:39], s[10:11], 0, v[36:37]
	v_lshl_add_u64 v[36:37], s[12:13], 0, v[36:37]
	v_lshl_add_u64 v[34:35], v[34:35], 0, s[50:51]
	global_load_dwordx4 v[8:11], v[10:11], off
	s_nop 0
	global_load_dwordx2 v[30:31], v[30:31], off
	v_lshl_add_u64 v[28:29], v[34:35], 0, v[28:29]
	global_load_dwordx2 v[32:33], v[32:33], off
	s_nop 0
	global_load_dwordx2 v[34:35], v[38:39], off
	s_nop 0
	global_load_dwordx2 v[36:37], v[36:37], off
	s_nop 0
	global_load_dwordx2 v[38:39], v[28:29], off
	v_mov_b32_e32 v3, v1
	v_mov_b64_e32 v[28:29], v[0:1]
	s_cbranch_execz .LBB0_760
	s_branch .LBB0_761

; __device__ __forceinline__ float bf_lo(unsigned w) { return __uint_as_float(w << 16); }
; __device__ __forceinline__ float bf_hi(unsigned w) { return __uint_as_float(w & 0xffff0000u); }
; __device__ __forceinline__ void rwkv_scan(const Params& p, LAS unsigned char* lds, int rowbase, int T, int h, int q4, const float* S0, float* Sout) {
;     ...
;     const bool ldr = w >= 4; const int lt = tid & 255, lstep = lt >> 4, lj = lt & 15;
;     f32x4 gd[2]; u32x2 gk[2], ga[2], gp[2], gr[2], gv[2];
;     auto gload = [&](int c) {
;         if (ldr) {
; #pragma unroll
;             for (int q = 0; q < 2; ++q) {
;                 const size_t row = (size_t)(rowbase + c * 32 + lstep + q * 16); const size_t o = row * 512 + h * 64 + lj * 4;
;                 gd[q] = *(const f32x4*)(decay + o); gk[q] = *(const u32x2*)(kk + o); ga[q] = *(const u32x2*)(kka + o); gp[q] = *(const u32x2*)(kp + o); gr[q] = *(const u32x2*)(rb + o);
;                 gv[q] = *(const u32x2*)(vb + row * 512 + h * 64 + q4 * 16 + (lj & 3) * 4);
;             }
;         }
;     };
;     auto up4 = [](const u32x2 x) { return (f32x4){bf_lo(x.x), bf_hi(x.x), bf_lo(x.y), bf_hi(x.y)}; };
;     float selv[16];
; #pragma unroll
;     for (int i = 0; i < 16; ++i) selv[i] = (seg == i) ? 1.0f : 0.0f;
;     const int nch = T / 32;
;     gload(0);
.LBB0_761:
	v_cmp_eq_u32_e32 vcc, 0, v12
	v_lshrrev_b32_e32 v0, 4, v14
	v_and_b32_e32 v0, 3, v0
	v_cndmask_b32_e64 v46, 0, 1.0, vcc
	v_cmp_eq_u32_e32 vcc, 1, v12
	s_lshl_b32 s4, s46, 2
	s_lshl_b64 s[50:51], s[22:23], 1
	v_cndmask_b32_e64 v47, 0, 1.0, vcc
	v_cmp_eq_u32_e32 vcc, 2, v12
	v_and_or_b32 v0, s4, 12, v0
	s_add_u32 s22, s16, s50
	v_cndmask_b32_e64 v48, 0, 1.0, vcc
	v_cmp_eq_u32_e32 vcc, 3, v12
	v_or_b32_e32 v17, s43, v0
	s_addc_u32 s47, s17, s51
	v_cndmask_b32_e64 v49, 0, 1.0, vcc
	v_cmp_eq_u32_e32 vcc, 4, v12
	s_lshl_b32 s43, s43, 1
	s_add_u32 s52, s22, s43
	v_cndmask_b32_e64 v50, 0, 1.0, vcc
	v_cmp_eq_u32_e32 vcc, 5, v12
	s_addc_u32 s53, s47, 0
	v_lshlrev_b32_e32 v63, 2, v0
	v_cndmask_b32_e64 v51, 0, 1.0, vcc
	v_cmp_eq_u32_e32 vcc, 6, v12
	v_or_b32_e32 v0, 1, v13
	s_add_u32 s50, s18, s50
	v_cndmask_b32_e64 v52, 0, 1.0, vcc
	v_cmp_eq_u32_e32 vcc, 7, v12
	v_lshl_add_u64 v[40:41], v[2:3], 1, s[52:53]
	v_lshlrev_b32_e32 v66, 8, v0
	v_cndmask_b32_e64 v53, 0, 1.0, vcc
	v_cmp_eq_u32_e32 vcc, 8, v12
	v_lshlrev_b32_e32 v67, 6, v0
	s_addc_u32 s51, s19, s51
	v_cndmask_b32_e64 v54, 0, 1.0, vcc
	v_cmp_eq_u32_e32 vcc, 9, v12
	v_lshlrev_b32_e32 v0, 1, v17
	v_mov_b32_e32 v2, v1
	v_cndmask_b32_e64 v55, 0, 1.0, vcc
	v_cmp_eq_u32_e32 vcc, 10, v12
	v_mov_b32_e32 v3, v1
	v_lshlrev_b32_e32 v62, 4, v12
	v_cndmask_b32_e64 v56, 0, 1.0, vcc
	v_cmp_eq_u32_e32 vcc, 11, v12
	v_cmp_gt_u32_e64 s[4:5], 4, v12
	v_lshlrev_b32_e32 v64, 8, v13
	v_cndmask_b32_e64 v57, 0, 1.0, vcc
	v_cmp_eq_u32_e32 vcc, 12, v12
	v_lshlrev_b32_e32 v65, 6, v13
	v_lshl_add_u64 v[42:43], s[50:51], 0, v[0:1]
	v_cndmask_b32_e64 v58, 0, 1.0, vcc
	v_cmp_eq_u32_e32 vcc, 13, v12
	v_add_u32_e32 v68, s42, v12
	v_add_u32_e32 v69, s42, v13
	v_cndmask_b32_e64 v59, 0, 1.0, vcc
	v_cmp_eq_u32_e32 vcc, 14, v12
	v_mov_b32_e32 v0, v1
	s_mov_b32 s46, 0
	v_cndmask_b32_e64 v60, 0, 1.0, vcc
	v_cmp_eq_u32_e32 vcc, 15, v12
	v_mov_b64_e32 v[14:15], v[2:3]
	v_mov_b64_e32 v[12:13], v[0:1]
	v_cndmask_b32_e64 v61, 0, 1.0, vcc
	s_mov_b32 s22, 0
	s_mov_b32 s98, 0xcccccccc
	s_mov_b32 s99, 0xcccccccc
	s_mov_b32 s100, 0xaaaaaaaa
	s_mov_b32 s101, 0xaaaaaaaa
	s_branch .LBB0_763

; #define LAS __attribute__((address_space(3)))
; __device__ __forceinline__ void rwkv_scan(const Params& p, LAS unsigned char* lds, int rowbase, int T, int h, int q4, const float* S0, float* Sout) {
;     ...
;         if (ldr) {
; #pragma unroll
;             for (int q = 0; q < 2; ++q) {
;                 const int st_ = lstep + q * 16;
;                 *(LAS f32x4*)(b + st_ * 256 + lj * 16) = gd[q];
;                 *(LAS f32x4*)(b + 8192 + st_ * 256 + lj * 16) = up4(gk[q]);
;                 *(LAS f32x4*)(b + 16384 + st_ * 256 + lj * 16) = up4(ga[q]);
;                 *(LAS f32x4*)(b + 24576 + st_ * 256 + lj * 16) = up4(gp[q]);
;                 *(LAS f32x4*)(b + 32768 + st_ * 256 + lj * 16) = up4(gr[q]);
;                 if (lj < 4) *(LAS f32x4*)(b + 40960 + st_ * 64 + lj * 16) = up4(gv[q]);
;             }
;         }
.LBB0_763:
	s_bitcmp1_b32 s22, 0
	s_cselect_b32 s42, 0xa800, 0
	s_add_i32 s47, s42, 0
	s_andn2_b64 vcc, exec, s[38:39]
	v_add_u32_e32 v0, s47, v62
	s_cbranch_vccnz .LBB0_769
	v_add_u32_e32 v2, v0, v64
	v_add_u32_e32 v3, v0, v66
	s_waitcnt vmcnt(0)
	v_pk_mul_f32 v[74:75], v[4:5], v[8:9]
	v_pk_mul_f32 v[76:77], v[6:7], v[10:11]
	v_rcp_f32_e32 v78, v4
	v_rcp_f32_e32 v79, v5
	v_rcp_f32_e32 v80, v6
	v_rcp_f32_e32 v81, v7
	v_lshlrev_b32_e32 v70, 16, v18
	v_and_b32_e32 v71, 0xffff0000, v18
	v_lshlrev_b32_e32 v72, 16, v19
	v_and_b32_e32 v73, 0xffff0000, v19
	v_rcp_f32_e32 v82, v74
	v_rcp_f32_e32 v83, v75
	v_rcp_f32_e32 v84, v76
	v_rcp_f32_e32 v85, v77
	ds_write_b128 v2, v[74:77]
	ds_write_b128 v2, v[70:73] offset:8192
	v_lshlrev_b32_e32 v86, 16, v30
	v_and_b32_e32 v87, 0xffff0000, v30
	v_lshlrev_b32_e32 v88, 16, v31
	v_and_b32_e32 v89, 0xffff0000, v31
	v_pk_mul_f32 v[86:87], v[86:87], v[4:5]
	v_pk_mul_f32 v[88:89], v[88:89], v[6:7]
	ds_write_b128 v3, v[86:89] offset:8192
	v_lshlrev_b32_e32 v90, 16, v20
	v_and_b32_e32 v91, 0xffff0000, v20
	v_lshlrev_b32_e32 v92, 16, v21
	v_and_b32_e32 v93, 0xffff0000, v21
	v_pk_mul_f32 v[90:91], v[90:91], v[78:79]
	v_pk_mul_f32 v[92:93], v[92:93], v[80:81]
	ds_write_b128 v2, v[90:93] offset:16384
	v_lshlrev_b32_e32 v94, 16, v32
	v_and_b32_e32 v95, 0xffff0000, v32
	v_lshlrev_b32_e32 v96, 16, v33
	v_and_b32_e32 v97, 0xffff0000, v33
	v_pk_mul_f32 v[94:95], v[94:95], v[82:83]
	v_pk_mul_f32 v[96:97], v[96:97], v[84:85]
	ds_write_b128 v3, v[94:97] offset:16384
	v_lshlrev_b32_e32 v98, 16, v22
	v_and_b32_e32 v99, 0xffff0000, v22
	v_lshlrev_b32_e32 v100, 16, v23
	v_and_b32_e32 v101, 0xffff0000, v23
	v_pk_mul_f32 v[98:99], v[98:99], v[78:79]
	v_pk_mul_f32 v[100:101], v[100:101], v[80:81]
	ds_write_b128 v2, v[98:101] offset:24576
	v_lshlrev_b32_e32 v102, 16, v34
	v_and_b32_e32 v103, 0xffff0000, v34
	v_lshlrev_b32_e32 v104, 16, v35
	v_and_b32_e32 v105, 0xffff0000, v35
	v_pk_mul_f32 v[102:103], v[102:103], v[82:83]
	v_pk_mul_f32 v[104:105], v[104:105], v[84:85]
	ds_write_b128 v3, v[102:105] offset:24576
	v_lshlrev_b32_e32 v106, 16, v24
	v_and_b32_e32 v107, 0xffff0000, v24
	v_lshlrev_b32_e32 v108, 16, v25
	v_and_b32_e32 v109, 0xffff0000, v25
	v_pk_mul_f32 v[106:107], v[106:107], v[4:5]
	v_pk_mul_f32 v[108:109], v[108:109], v[6:7]
	ds_write_b128 v2, v[106:109] offset:32768
	v_lshlrev_b32_e32 v110, 16, v36
	v_and_b32_e32 v111, 0xffff0000, v36
	v_lshlrev_b32_e32 v112, 16, v37
	v_and_b32_e32 v113, 0xffff0000, v37
	v_pk_mul_f32 v[110:111], v[110:111], v[74:75]
	v_pk_mul_f32 v[112:113], v[112:113], v[76:77]
	ds_write_b128 v3, v[110:113] offset:32768
	s_and_saveexec_b64 s[42:43], s[4:5]
	v_lshlrev_b32_e32 v114, 16, v26
	v_and_b32_e32 v115, 0xffff0000, v26
	v_lshlrev_b32_e32 v116, 16, v27
	v_and_b32_e32 v117, 0xffff0000, v27
	v_add_u32_e32 v2, v0, v65
	ds_write_b128 v2, v[114:117] offset:40960
	v_lshlrev_b32_e32 v118, 16, v38
	v_and_b32_e32 v119, 0xffff0000, v38
	v_lshlrev_b32_e32 v120, 16, v39
	v_and_b32_e32 v121, 0xffff0000, v39
	v_add_u32_e32 v3, v0, v67
	ds_write_b128 v3, v[118:121] offset:40960
	s_or_b64 exec, exec, s[42:43]

; #define LAS __attribute__((address_space(3)))
; #define RW_LD(X, s) do { X.d = *(const LAS f32x4*)(bs + (s) * 256); X.k = *(const LAS f32x4*)(bs + 8192 + (s) * 256); X.a = *(const LAS f32x4*)(bs + 16384 + (s) * 256); \
;                          X.p = *(const LAS f32x4*)(bs + 24576 + (s) * 256); X.r = *(const LAS f32x4*)(bs + 32768 + (s) * 256); X.v = *(const LAS float*)(bv + (s) * 64); } while (0)
; #define RW_STEP(X, s) do { float sa = fmaf(S[3], X.k[3], fmaf(S[2], X.k[2], fmaf(S[1], X.k[1], S[0] * X.k[0]))); const f32x4 T = S * X.d + X.v * X.p; sa = -red16(sa); \
;                            S = T + sa * X.a; float y = fmaf(S[3], X.r[3], fmaf(S[2], X.r[2], fmaf(S[1], X.r[1], S[0] * X.r[0]))); y = red16(y); \
;                            yk = fmaf(selv[(s) & 15], y, yk); } while (0)
; #define RW_YST(s) do { if ((s) == 15) { ob[(size_t)(rowbase + c * 32 + seg) * D + 512 + h * 64 + vrow] = f2bf(yk); yk = 0.f; } } while (0)
; __device__ __forceinline__ void rwkv_scan(const Params& p, LAS unsigned char* lds, int rowbase, int T, int h, int q4, const float* S0, float* Sout) {
;     ...
;     auto gload = [&](int c) {
;         if (ldr) {
; #pragma unroll
;             for (int q = 0; q < 2; ++q) {
;                 const size_t row = (size_t)(rowbase + c * 32 + lstep + q * 16); const size_t o = row * 512 + h * 64 + lj * 4;
;                 gd[q] = *(const f32x4*)(decay + o); gk[q] = *(const u32x2*)(kk + o); ga[q] = *(const u32x2*)(kka + o); gp[q] = *(const u32x2*)(kp + o); gr[q] = *(const u32x2*)(rb + o);
;                 gv[q] = *(const u32x2*)(vb + row * 512 + h * 64 + q4 * 16 + (lj & 3) * 4);
;             }
;         }
;     };
;     ...
;             const LAS unsigned char* bs = b + seg * 16; const LAS unsigned char* bv = b + 40960 + vloc * 4;
;     ...
;             RwStep xa, xb, xc; float yk = 0.f;
;     ...
;             RW_LD(xa, 0); RW_LD(xb, 1);
; #pragma unroll
;             for (int s = 0; s < 30; s += 3) {
;                 RW_LD(xc, s + 2); RW_STEP(xa, s); RW_YST(s);
;                 RW_LD(xa, s + 3); RW_STEP(xb, s + 1); RW_YST(s + 1);
.LBB0_771:
	s_waitcnt vmcnt(4)
	v_add_u32_e32 v30, s46, v69
	v_add_u32_e32 v2, 32, v30
	v_ashrrev_i32_e32 v3, 31, v2
	v_lshlrev_b64 v[4:5], 9, v[2:3]
	v_or_b32_e32 v5, v5, v29
	v_or_b32_e32 v4, v4, v28
	v_lshlrev_b64 v[8:9], 1, v[4:5]
	v_lshl_add_u64 v[6:7], v[4:5], 2, s[90:91]
	v_lshl_add_u64 v[10:11], s[6:7], 0, v[8:9]
	global_load_dwordx4 v[4:7], v[6:7], off
	s_nop 0
	global_load_dwordx2 v[18:19], v[10:11], off
	v_lshl_add_u64 v[10:11], s[8:9], 0, v[8:9]
	v_lshlrev_b64 v[2:3], 10, v[2:3]
	global_load_dwordx2 v[20:21], v[10:11], off
	v_lshl_add_u64 v[10:11], s[10:11], 0, v[8:9]
	v_lshl_add_u64 v[2:3], v[40:41], 0, v[2:3]
	v_lshl_add_u64 v[8:9], s[12:13], 0, v[8:9]
	global_load_dwordx2 v[22:23], v[10:11], off
	global_load_dwordx2 v[24:25], v[8:9], off
	global_load_dwordx2 v[26:27], v[2:3], off
	v_add_u32_e32 v2, 33, v30
	v_ashrrev_i32_e32 v3, 31, v2
	v_lshlrev_b64 v[8:9], 9, v[2:3]
	v_or_b32_e32 v9, v9, v29
	v_or_b32_e32 v8, v8, v28
	s_waitcnt vmcnt(8)
	v_lshlrev_b64 v[34:35], 1, v[8:9]
	v_lshl_add_u64 v[10:11], v[8:9], 2, s[90:91]
	v_lshl_add_u64 v[30:31], s[6:7], 0, v[34:35]
	v_lshl_add_u64 v[32:33], s[8:9], 0, v[34:35]
	s_waitcnt vmcnt(7)
	v_lshl_add_u64 v[36:37], s[10:11], 0, v[34:35]
	s_waitcnt vmcnt(6)
	v_lshl_add_u64 v[38:39], s[12:13], 0, v[34:35]
	v_lshlrev_b64 v[2:3], 10, v[2:3]
	global_load_dwordx4 v[8:11], v[10:11], off
	s_nop 0
	global_load_dwordx2 v[30:31], v[30:31], off
	v_lshl_add_u64 v[2:3], v[40:41], 0, v[2:3]
	global_load_dwordx2 v[32:33], v[32:33], off
	s_nop 0
	global_load_dwordx2 v[34:35], v[36:37], off
	s_nop 0
	global_load_dwordx2 v[36:37], v[38:39], off
	s_nop 0
	global_load_dwordx2 v[38:39], v[2:3], off
	s_andn2_b64 vcc, exec, s[30:31]
	s_cbranch_vccnz .LBB0_762
.LBB0_772:
	v_mov_b32_e32 v70, v0
	v_add_u32_e32 v71, s47, v63
	v_add_u32_e32 v71, 0xa000, v71
	v_add_u32_e32 v2, 0x400, v71
	ds_read_b128 v[76:79], v70 offset:8192
	ds_read_b128 v[84:87], v70 offset:24576
	ds_read_b128 v[80:83], v70 offset:16384
	ds_read_b128 v[88:91], v70 offset:32768
	ds_read_b128 v[24:27], v70 offset:0
	ds_read2_b32 v[136:137], v71 offset0:0 offset1:16
	ds_read_b128 v[92:95], v70 offset:8448
	ds_read_b128 v[100:103], v70 offset:24832
	ds_read_b128 v[96:99], v70 offset:16640
	ds_read_b128 v[104:107], v70 offset:33024
	v_add_u32_e32 v196, s46, v68
	v_mov_b32_e32 v197, 0
	s_waitcnt lgkmcnt(4)
	v_pk_mul_f32 v[72:73], v[12:13], v[76:77]
	v_pk_fma_f32 v[72:73], v[14:15], v[78:79], v[72:73]
	v_pk_fma_f32 v[140:141], v[136:137], v[84:85], v[12:13] op_sel_hi:[0,1,1]
	v_add_f32_e32 v74, v72, v73
	v_pk_fma_f32 v[142:143], v[136:137], v[86:87], v[14:15] op_sel_hi:[0,1,1]
	ds_read_b128 v[108:111], v70 offset:8704
	v_add_f32_dpp v74, v74, v74 quad_perm:[1,0,3,2] row_mask:0xf bank_mask:0xf bound_ctrl:1
	ds_read_b128 v[116:119], v70 offset:25088
	ds_read_b128 v[112:115], v70 offset:16896
	v_add_f32_dpp v74, v74, v74 quad_perm:[2,3,0,1] row_mask:0xf bank_mask:0xf bound_ctrl:1
	ds_read_b128 v[120:123], v70 offset:33280
	ds_read_b128 v[28:31], v70 offset:512
	v_add_f32_dpp v74, v74, v74 row_half_mirror row_mask:0xf bank_mask:0xf bound_ctrl:1
	ds_read2_b32 v[138:139], v71 offset0:32 offset1:48
	s_nop 0
	v_add_f32_dpp v74, v74, v74 row_mirror row_mask:0xf bank_mask:0xf bound_ctrl:1
	v_pk_fma_f32 v[12:13], v[80:81], v[74:75], v[140:141] op_sel_hi:[1,0,1] neg_lo:[0,1,0] neg_hi:[0,1,0]
	v_pk_fma_f32 v[14:15], v[82:83], v[74:75], v[142:143] op_sel_hi:[1,0,1] neg_lo:[0,1,0] neg_hi:[0,1,0]
	s_waitcnt lgkmcnt(6)
	v_pk_mul_f32 v[72:73], v[12:13], v[92:93]
	v_pk_fma_f32 v[72:73], v[14:15], v[94:95], v[72:73]
	v_pk_fma_f32 v[140:141], v[136:137], v[100:101], v[12:13] op_sel:[1,0,0] op_sel_hi:[1,1,1]
	v_add_f32_e32 v74, v72, v73
	v_pk_fma_f32 v[142:143], v[136:137], v[102:103], v[14:15] op_sel:[1,0,0] op_sel_hi:[1,1,1]
	v_pk_mul_f32 v[198:199], v[12:13], v[88:89]
	v_add_f32_dpp v74, v74, v74 quad_perm:[1,0,3,2] row_mask:0xf bank_mask:0xf bound_ctrl:1
	v_pk_fma_f32 v[198:199], v[14:15], v[90:91], v[198:199]
	v_add_f32_e32 v144, v198, v199
	v_add_f32_dpp v74, v74, v74 quad_perm:[2,3,0,1] row_mask:0xf bank_mask:0xf bound_ctrl:1
	ds_read_b128 v[76:79], v70 offset:8960
	ds_read_b128 v[84:87], v70 offset:25344
	v_add_f32_dpp v74, v74, v74 row_half_mirror row_mask:0xf bank_mask:0xf bound_ctrl:1
	ds_read_b128 v[80:83], v70 offset:17152
	ds_read_b128 v[88:91], v70 offset:33536
	v_add_f32_dpp v74, v74, v74 row_mirror row_mask:0xf bank_mask:0xf bound_ctrl:1
	v_pk_fma_f32 v[12:13], v[96:97], v[74:75], v[140:141] op_sel_hi:[1,0,1] neg_lo:[0,1,0] neg_hi:[0,1,0]
	v_pk_fma_f32 v[14:15], v[98:99], v[74:75], v[142:143] op_sel_hi:[1,0,1] neg_lo:[0,1,0] neg_hi:[0,1,0]
	v_pk_mul_f32 v[20:21], v[12:13], v[24:25]
	v_pk_mul_f32 v[22:23], v[14:15], v[26:27]
	s_waitcnt lgkmcnt(4)
	v_pk_mul_f32 v[72:73], v[20:21], v[108:109]
	v_pk_fma_f32 v[72:73], v[22:23], v[110:111], v[72:73]
	v_pk_fma_f32 v[140:141], v[138:139], v[116:117], v[20:21] op_sel_hi:[0,1,1]
	v_add_f32_e32 v74, v72, v73
	v_pk_fma_f32 v[142:143], v[138:139], v[118:119], v[22:23] op_sel_hi:[0,1,1]
	v_pk_mul_f32 v[198:199], v[12:13], v[104:105]
	v_add_f32_dpp v74, v74, v74 quad_perm:[1,0,3,2] row_mask:0xf bank_mask:0xf bound_ctrl:1
	v_pk_fma_f32 v[198:199], v[14:15], v[106:107], v[198:199]
	v_add_f32_e32 v145, v198, v199
	v_add_f32_dpp v74, v74, v74 quad_perm:[2,3,0,1] row_mask:0xf bank_mask:0xf bound_ctrl:1
	ds_read_b128 v[92:95], v70 offset:9216
	ds_read_b128 v[100:103], v70 offset:25600
	v_add_f32_dpp v74, v74, v74 row_half_mirror row_mask:0xf bank_mask:0xf bound_ctrl:1
	ds_read_b128 v[96:99], v70 offset:17408
	ds_read_b128 v[104:107], v70 offset:33792
	v_add_f32_dpp v74, v74, v74 row_mirror row_mask:0xf bank_mask:0xf bound_ctrl:1
	v_pk_fma_f32 v[20:21], v[112:113], v[74:75], v[140:141] op_sel_hi:[1,0,1] neg_lo:[0,1,0] neg_hi:[0,1,0]
	v_pk_fma_f32 v[22:23], v[114:115], v[74:75], v[142:143] op_sel_hi:[1,0,1] neg_lo:[0,1,0] neg_hi:[0,1,0]
	ds_read_b128 v[24:27], v70 offset:1024
	ds_read2_b32 v[136:137], v71 offset0:64 offset1:80
	s_waitcnt lgkmcnt(6)
; #define RW_LD(X, s) do { X.d = *(const LAS f32x4*)(bs + (s) * 256); X.k = *(const LAS f32x4*)(bs + 8192 + (s) * 256); X.a = *(const LAS f32x4*)(bs + 16384 + (s) * 256); \
;                          X.p = *(const LAS f32x4*)(bs + 24576 + (s) * 256); X.r = *(const LAS f32x4*)(bs + 32768 + (s) * 256); X.v = *(const LAS float*)(bv + (s) * 64); } while (0)
; #define RW_STEP(X, s) do { float sa = fmaf(S[3], X.k[3], fmaf(S[2], X.k[2], fmaf(S[1], X.k[1], S[0] * X.k[0]))); const f32x4 T = S * X.d + X.v * X.p; sa = -red16(sa); \
;                            S = T + sa * X.a; float y = fmaf(S[3], X.r[3], fmaf(S[2], X.r[2], fmaf(S[1], X.r[1], S[0] * X.r[0]))); y = red16(y); \
;                            yk = fmaf(selv[(s) & 15], y, yk); } while (0)
; #define RW_YST(s) do { if ((s) == 15) { ob[(size_t)(rowbase + c * 32 + seg) * D + 512 + h * 64 + vrow] = f2bf(yk); yk = 0.f; } } while (0)
; __device__ __forceinline__ void rwkv_scan(const Params& p, LAS unsigned char* lds, int rowbase, int T, int h, int q4, const float* S0, float* Sout) {
;     ...
;             RwStep xa, xb, xc; float yk = 0.f;
;     ...
;             RW_LD(xa, 0); RW_LD(xb, 1);
; #pragma unroll
;             for (int s = 0; s < 30; s += 3) {
;                 RW_LD(xc, s + 2); RW_STEP(xa, s); RW_YST(s);
;                 RW_LD(xa, s + 3); RW_STEP(xb, s + 1); RW_YST(s + 1);
	v_pk_mul_f32 v[72:73], v[20:21], v[76:77]
	v_pk_fma_f32 v[72:73], v[22:23], v[78:79], v[72:73]
	v_pk_fma_f32 v[140:141], v[138:139], v[84:85], v[20:21] op_sel:[1,0,0] op_sel_hi:[1,1,1]
	v_add_f32_e32 v74, v72, v73
	v_pk_fma_f32 v[142:143], v[138:139], v[86:87], v[22:23] op_sel:[1,0,0] op_sel_hi:[1,1,1]
	v_pk_mul_f32 v[198:199], v[20:21], v[120:121]
	v_add_f32_dpp v74, v74, v74 quad_perm:[1,0,3,2] row_mask:0xf bank_mask:0xf bound_ctrl:1
	v_pk_fma_f32 v[198:199], v[22:23], v[122:123], v[198:199]
	v_add_f32_e32 v146, v198, v199
	v_add_f32_dpp v74, v74, v74 quad_perm:[2,3,0,1] row_mask:0xf bank_mask:0xf bound_ctrl:1
	ds_read_b128 v[108:111], v70 offset:9472
	ds_read_b128 v[116:119], v70 offset:25856
	v_add_f32_dpp v74, v74, v74 row_half_mirror row_mask:0xf bank_mask:0xf bound_ctrl:1
	ds_read_b128 v[112:115], v70 offset:17664
	ds_read_b128 v[120:123], v70 offset:34048
	v_add_f32_dpp v74, v74, v74 row_mirror row_mask:0xf bank_mask:0xf bound_ctrl:1
	v_pk_fma_f32 v[20:21], v[80:81], v[74:75], v[140:141] op_sel_hi:[1,0,1] neg_lo:[0,1,0] neg_hi:[0,1,0]
	v_pk_fma_f32 v[22:23], v[82:83], v[74:75], v[142:143] op_sel_hi:[1,0,1] neg_lo:[0,1,0] neg_hi:[0,1,0]
	v_pk_mul_f32 v[12:13], v[20:21], v[28:29]
	v_pk_mul_f32 v[14:15], v[22:23], v[30:31]
	s_waitcnt lgkmcnt(4)
	v_pk_mul_f32 v[72:73], v[12:13], v[92:93]
	v_pk_fma_f32 v[72:73], v[14:15], v[94:95], v[72:73]
	v_pk_fma_f32 v[140:141], v[136:137], v[100:101], v[12:13] op_sel_hi:[0,1,1]
	v_add_f32_e32 v74, v72, v73
	v_pk_fma_f32 v[142:143], v[136:137], v[102:103], v[14:15] op_sel_hi:[0,1,1]
	v_pk_mul_f32 v[198:199], v[20:21], v[88:89]
	v_add_f32_dpp v74, v74, v74 quad_perm:[1,0,3,2] row_mask:0xf bank_mask:0xf bound_ctrl:1
	v_pk_fma_f32 v[198:199], v[22:23], v[90:91], v[198:199]
	v_add_f32_e32 v147, v198, v199
	v_add_f32_dpp v74, v74, v74 quad_perm:[2,3,0,1] row_mask:0xf bank_mask:0xf bound_ctrl:1
	ds_read_b128 v[76:79], v70 offset:9728
	ds_read_b128 v[84:87], v70 offset:26112
	v_add_f32_dpp v74, v74, v74 row_half_mirror row_mask:0xf bank_mask:0xf bound_ctrl:1
	ds_read_b128 v[80:83], v70 offset:17920
	ds_read_b128 v[88:91], v70 offset:34304
	v_add_f32_dpp v74, v74, v74 row_mirror row_mask:0xf bank_mask:0xf bound_ctrl:1
	v_pk_fma_f32 v[12:13], v[96:97], v[74:75], v[140:141] op_sel_hi:[1,0,1] neg_lo:[0,1,0] neg_hi:[0,1,0]
	v_pk_fma_f32 v[14:15], v[98:99], v[74:75], v[142:143] op_sel_hi:[1,0,1] neg_lo:[0,1,0] neg_hi:[0,1,0]
	ds_read_b128 v[28:31], v70 offset:1536
	ds_read2_b32 v[138:139], v71 offset0:96 offset1:112
	s_waitcnt lgkmcnt(6)
	v_pk_mul_f32 v[72:73], v[12:13], v[108:109]
	v_pk_fma_f32 v[72:73], v[14:15], v[110:111], v[72:73]
	v_pk_fma_f32 v[140:141], v[136:137], v[116:117], v[12:13] op_sel:[1,0,0] op_sel_hi:[1,1,1]
	v_add_f32_e32 v74, v72, v73
	v_pk_fma_f32 v[142:143], v[136:137], v[118:119], v[14:15] op_sel:[1,0,0] op_sel_hi:[1,1,1]
	v_pk_mul_f32 v[198:199], v[12:13], v[104:105]
	v_add_f32_dpp v74, v74, v74 quad_perm:[1,0,3,2] row_mask:0xf bank_mask:0xf bound_ctrl:1
	v_pk_fma_f32 v[198:199], v[14:15], v[106:107], v[198:199]
	v_add_f32_e32 v148, v198, v199
	v_add_f32_dpp v74, v74, v74 quad_perm:[2,3,0,1] row_mask:0xf bank_mask:0xf bound_ctrl:1
	ds_read_b128 v[92:95], v70 offset:9984
	ds_read_b128 v[100:103], v70 offset:26368
	v_add_f32_dpp v74, v74, v74 row_half_mirror row_mask:0xf bank_mask:0xf bound_ctrl:1
	ds_read_b128 v[96:99], v70 offset:18176
	ds_read_b128 v[104:107], v70 offset:34560
	v_add_f32_dpp v74, v74, v74 row_mirror row_mask:0xf bank_mask:0xf bound_ctrl:1
	v_pk_fma_f32 v[12:13], v[112:113], v[74:75], v[140:141] op_sel_hi:[1,0,1] neg_lo:[0,1,0] neg_hi:[0,1,0]
	v_pk_fma_f32 v[14:15], v[114:115], v[74:75], v[142:143] op_sel_hi:[1,0,1] neg_lo:[0,1,0] neg_hi:[0,1,0]
	v_pk_mul_f32 v[20:21], v[12:13], v[24:25]
	v_pk_mul_f32 v[22:23], v[14:15], v[26:27]
	s_waitcnt lgkmcnt(4)
	v_pk_mul_f32 v[72:73], v[20:21], v[76:77]
	v_pk_fma_f32 v[72:73], v[22:23], v[78:79], v[72:73]
	v_pk_fma_f32 v[140:141], v[138:139], v[84:85], v[20:21] op_sel_hi:[0,1,1]
	v_add_f32_e32 v74, v72, v73
	v_pk_fma_f32 v[142:143], v[138:139], v[86:87], v[22:23] op_sel_hi:[0,1,1]
	v_pk_mul_f32 v[198:199], v[12:13], v[120:121]
	v_add_f32_dpp v74, v74, v74 quad_perm:[1,0,3,2] row_mask:0xf bank_mask:0xf bound_ctrl:1
	v_pk_fma_f32 v[198:199], v[14:15], v[122:123], v[198:199]
	v_add_f32_e32 v149, v198, v199
	v_add_f32_dpp v74, v74, v74 quad_perm:[2,3,0,1] row_mask:0xf bank_mask:0xf bound_ctrl:1
	ds_read_b128 v[108:111], v70 offset:10240
	ds_read_b128 v[116:119], v70 offset:26624
	v_add_f32_dpp v74, v74, v74 row_half_mirror row_mask:0xf bank_mask:0xf bound_ctrl:1
	ds_read_b128 v[112:115], v70 offset:18432
	ds_read_b128 v[120:123], v70 offset:34816
	v_add_f32_dpp v74, v74, v74 row_mirror row_mask:0xf bank_mask:0xf bound_ctrl:1
	v_pk_fma_f32 v[20:21], v[80:81], v[74:75], v[140:141] op_sel_hi:[1,0,1] neg_lo:[0,1,0] neg_hi:[0,1,0]
	v_pk_fma_f32 v[22:23], v[82:83], v[74:75], v[142:143] op_sel_hi:[1,0,1] neg_lo:[0,1,0] neg_hi:[0,1,0]
	ds_read_b128 v[24:27], v70 offset:2048
	ds_read2_b32 v[136:137], v71 offset0:128 offset1:144
	s_waitcnt lgkmcnt(6)
; #define RW_LD(X, s) do { X.d = *(const LAS f32x4*)(bs + (s) * 256); X.k = *(const LAS f32x4*)(bs + 8192 + (s) * 256); X.a = *(const LAS f32x4*)(bs + 16384 + (s) * 256); \
;                          X.p = *(const LAS f32x4*)(bs + 24576 + (s) * 256); X.r = *(const LAS f32x4*)(bs + 32768 + (s) * 256); X.v = *(const LAS float*)(bv + (s) * 64); } while (0)
; #define RW_STEP(X, s) do { float sa = fmaf(S[3], X.k[3], fmaf(S[2], X.k[2], fmaf(S[1], X.k[1], S[0] * X.k[0]))); const f32x4 T = S * X.d + X.v * X.p; sa = -red16(sa); \
;                            S = T + sa * X.a; float y = fmaf(S[3], X.r[3], fmaf(S[2], X.r[2], fmaf(S[1], X.r[1], S[0] * X.r[0]))); y = red16(y); \
;                            yk = fmaf(selv[(s) & 15], y, yk); } while (0)
; #define RW_YST(s) do { if ((s) == 15) { ob[(size_t)(rowbase + c * 32 + seg) * D + 512 + h * 64 + vrow] = f2bf(yk); yk = 0.f; } } while (0)
; __device__ __forceinline__ void rwkv_scan(const Params& p, LAS unsigned char* lds, int rowbase, int T, int h, int q4, const float* S0, float* Sout) {
;     ...
;             RwStep xa, xb, xc; float yk = 0.f;
;     ...
;             RW_LD(xa, 0); RW_LD(xb, 1);
; #pragma unroll
;             for (int s = 0; s < 30; s += 3) {
;                 RW_LD(xc, s + 2); RW_STEP(xa, s); RW_YST(s);
;                 RW_LD(xa, s + 3); RW_STEP(xb, s + 1); RW_YST(s + 1);
;                 RW_LD(xb, s + 4); RW_STEP(xc, s + 2); RW_YST(s + 2);
;             }
	v_pk_mul_f32 v[72:73], v[20:21], v[92:93]
	v_pk_fma_f32 v[72:73], v[22:23], v[94:95], v[72:73]
	v_pk_fma_f32 v[140:141], v[138:139], v[100:101], v[20:21] op_sel:[1,0,0] op_sel_hi:[1,1,1]
	v_add_f32_e32 v74, v72, v73
	v_pk_fma_f32 v[142:143], v[138:139], v[102:103], v[22:23] op_sel:[1,0,0] op_sel_hi:[1,1,1]
	v_pk_mul_f32 v[198:199], v[20:21], v[88:89]
	v_add_f32_dpp v74, v74, v74 quad_perm:[1,0,3,2] row_mask:0xf bank_mask:0xf bound_ctrl:1
	v_pk_fma_f32 v[198:199], v[22:23], v[90:91], v[198:199]
	v_add_f32_e32 v150, v198, v199
	v_add_f32_dpp v74, v74, v74 quad_perm:[2,3,0,1] row_mask:0xf bank_mask:0xf bound_ctrl:1
	ds_read_b128 v[76:79], v70 offset:10496
	ds_read_b128 v[84:87], v70 offset:26880
	v_add_f32_dpp v74, v74, v74 row_half_mirror row_mask:0xf bank_mask:0xf bound_ctrl:1
	ds_read_b128 v[80:83], v70 offset:18688
	ds_read_b128 v[88:91], v70 offset:35072
	v_add_f32_dpp v74, v74, v74 row_mirror row_mask:0xf bank_mask:0xf bound_ctrl:1
	v_pk_fma_f32 v[20:21], v[96:97], v[74:75], v[140:141] op_sel_hi:[1,0,1] neg_lo:[0,1,0] neg_hi:[0,1,0]
	v_pk_fma_f32 v[22:23], v[98:99], v[74:75], v[142:143] op_sel_hi:[1,0,1] neg_lo:[0,1,0] neg_hi:[0,1,0]
	v_pk_mul_f32 v[12:13], v[20:21], v[28:29]
	v_pk_mul_f32 v[14:15], v[22:23], v[30:31]
	s_waitcnt lgkmcnt(4)
	v_pk_mul_f32 v[72:73], v[12:13], v[108:109]
	v_pk_fma_f32 v[72:73], v[14:15], v[110:111], v[72:73]
	v_pk_fma_f32 v[140:141], v[136:137], v[116:117], v[12:13] op_sel_hi:[0,1,1]
	v_add_f32_e32 v74, v72, v73
	v_pk_fma_f32 v[142:143], v[136:137], v[118:119], v[14:15] op_sel_hi:[0,1,1]
	v_pk_mul_f32 v[198:199], v[20:21], v[104:105]
	v_add_f32_dpp v74, v74, v74 quad_perm:[1,0,3,2] row_mask:0xf bank_mask:0xf bound_ctrl:1
	v_pk_fma_f32 v[198:199], v[22:23], v[106:107], v[198:199]
	v_add_f32_e32 v151, v198, v199
	v_add_f32_dpp v74, v74, v74 quad_perm:[2,3,0,1] row_mask:0xf bank_mask:0xf bound_ctrl:1
	ds_read_b128 v[92:95], v70 offset:10752
	ds_read_b128 v[100:103], v70 offset:27136
	v_add_f32_dpp v74, v74, v74 row_half_mirror row_mask:0xf bank_mask:0xf bound_ctrl:1
	ds_read_b128 v[96:99], v70 offset:18944
	ds_read_b128 v[104:107], v70 offset:35328
	v_add_f32_dpp v74, v74, v74 row_mirror row_mask:0xf bank_mask:0xf bound_ctrl:1
	v_pk_fma_f32 v[12:13], v[112:113], v[74:75], v[140:141] op_sel_hi:[1,0,1] neg_lo:[0,1,0] neg_hi:[0,1,0]
	v_pk_fma_f32 v[14:15], v[114:115], v[74:75], v[142:143] op_sel_hi:[1,0,1] neg_lo:[0,1,0] neg_hi:[0,1,0]
	ds_read_b128 v[28:31], v70 offset:2560
	ds_read2_b32 v[138:139], v71 offset0:160 offset1:176
	s_waitcnt lgkmcnt(6)
	v_pk_mul_f32 v[72:73], v[12:13], v[76:77]
	v_pk_fma_f32 v[72:73], v[14:15], v[78:79], v[72:73]
	v_pk_fma_f32 v[140:141], v[136:137], v[84:85], v[12:13] op_sel:[1,0,0] op_sel_hi:[1,1,1]
	v_add_f32_e32 v74, v72, v73
	v_pk_fma_f32 v[142:143], v[136:137], v[86:87], v[14:15] op_sel:[1,0,0] op_sel_hi:[1,1,1]
	v_pk_mul_f32 v[198:199], v[12:13], v[120:121]
	v_add_f32_dpp v74, v74, v74 quad_perm:[1,0,3,2] row_mask:0xf bank_mask:0xf bound_ctrl:1
	v_pk_fma_f32 v[198:199], v[14:15], v[122:123], v[198:199]
	v_add_f32_e32 v152, v198, v199
	v_add_f32_dpp v74, v74, v74 quad_perm:[2,3,0,1] row_mask:0xf bank_mask:0xf bound_ctrl:1
	ds_read_b128 v[108:111], v70 offset:11008
	ds_read_b128 v[116:119], v70 offset:27392
	v_add_f32_dpp v74, v74, v74 row_half_mirror row_mask:0xf bank_mask:0xf bound_ctrl:1
	ds_read_b128 v[112:115], v70 offset:19200
	ds_read_b128 v[120:123], v70 offset:35584
	v_add_f32_dpp v74, v74, v74 row_mirror row_mask:0xf bank_mask:0xf bound_ctrl:1
	v_pk_fma_f32 v[12:13], v[80:81], v[74:75], v[140:141] op_sel_hi:[1,0,1] neg_lo:[0,1,0] neg_hi:[0,1,0]
	v_pk_fma_f32 v[14:15], v[82:83], v[74:75], v[142:143] op_sel_hi:[1,0,1] neg_lo:[0,1,0] neg_hi:[0,1,0]
	v_pk_mul_f32 v[20:21], v[12:13], v[24:25]
	v_pk_mul_f32 v[22:23], v[14:15], v[26:27]
	v_add_f32_dpp v176, v144, v144 row_mirror row_mask:0xf bank_mask:0x3
	s_nop 1
	v_add_f32_dpp v176, v152, v152 row_mirror row_mask:0xf bank_mask:0xc
	s_waitcnt lgkmcnt(4)
	v_pk_mul_f32 v[72:73], v[20:21], v[92:93]
	v_pk_fma_f32 v[72:73], v[22:23], v[94:95], v[72:73]
	v_pk_fma_f32 v[140:141], v[138:139], v[100:101], v[20:21] op_sel_hi:[0,1,1]
	v_add_f32_e32 v74, v72, v73
	v_pk_fma_f32 v[142:143], v[138:139], v[102:103], v[22:23] op_sel_hi:[0,1,1]
	v_pk_mul_f32 v[198:199], v[12:13], v[88:89]
	v_add_f32_dpp v74, v74, v74 quad_perm:[1,0,3,2] row_mask:0xf bank_mask:0xf bound_ctrl:1
	v_pk_fma_f32 v[198:199], v[14:15], v[90:91], v[198:199]
	v_add_f32_e32 v153, v198, v199
	v_add_f32_dpp v74, v74, v74 quad_perm:[2,3,0,1] row_mask:0xf bank_mask:0xf bound_ctrl:1
	ds_read_b128 v[76:79], v70 offset:11264
	ds_read_b128 v[84:87], v70 offset:27648
	v_add_f32_dpp v74, v74, v74 row_half_mirror row_mask:0xf bank_mask:0xf bound_ctrl:1
	ds_read_b128 v[80:83], v70 offset:19456
	ds_read_b128 v[88:91], v70 offset:35840
	v_add_f32_dpp v74, v74, v74 row_mirror row_mask:0xf bank_mask:0xf bound_ctrl:1
	v_pk_fma_f32 v[20:21], v[96:97], v[74:75], v[140:141] op_sel_hi:[1,0,1] neg_lo:[0,1,0] neg_hi:[0,1,0]
	v_pk_fma_f32 v[22:23], v[98:99], v[74:75], v[142:143] op_sel_hi:[1,0,1] neg_lo:[0,1,0] neg_hi:[0,1,0]
	ds_read_b128 v[24:27], v70 offset:3072
	ds_read2_b32 v[136:137], v71 offset0:192 offset1:208
	v_add_f32_dpp v177, v145, v145 row_mirror row_mask:0xf bank_mask:0x3
	s_nop 1
	v_add_f32_dpp v177, v153, v153 row_mirror row_mask:0xf bank_mask:0xc
	s_waitcnt lgkmcnt(6)
; #define RW_LD(X, s) do { X.d = *(const LAS f32x4*)(bs + (s) * 256); X.k = *(const LAS f32x4*)(bs + 8192 + (s) * 256); X.a = *(const LAS f32x4*)(bs + 16384 + (s) * 256); \
;                          X.p = *(const LAS f32x4*)(bs + 24576 + (s) * 256); X.r = *(const LAS f32x4*)(bs + 32768 + (s) * 256); X.v = *(const LAS float*)(bv + (s) * 64); } while (0)
; #define RW_STEP(X, s) do { float sa = fmaf(S[3], X.k[3], fmaf(S[2], X.k[2], fmaf(S[1], X.k[1], S[0] * X.k[0]))); const f32x4 T = S * X.d + X.v * X.p; sa = -red16(sa); \
;                            S = T + sa * X.a; float y = fmaf(S[3], X.r[3], fmaf(S[2], X.r[2], fmaf(S[1], X.r[1], S[0] * X.r[0]))); y = red16(y); \
;                            yk = fmaf(selv[(s) & 15], y, yk); } while (0)
; #define RW_YST(s) do { if ((s) == 15) { ob[(size_t)(rowbase + c * 32 + seg) * D + 512 + h * 64 + vrow] = f2bf(yk); yk = 0.f; } } while (0)
; __device__ __forceinline__ void rwkv_scan(const Params& p, LAS unsigned char* lds, int rowbase, int T, int h, int q4, const float* S0, float* Sout) {
;     ...
;             RwStep xa, xb, xc; float yk = 0.f;
;     ...
;             RW_LD(xa, 0); RW_LD(xb, 1);
; #pragma unroll
;             for (int s = 0; s < 30; s += 3) {
;                 RW_LD(xc, s + 2); RW_STEP(xa, s); RW_YST(s);
;                 RW_LD(xa, s + 3); RW_STEP(xb, s + 1); RW_YST(s + 1);
;                 RW_LD(xb, s + 4); RW_STEP(xc, s + 2); RW_YST(s + 2);
;             }
	v_pk_mul_f32 v[72:73], v[20:21], v[108:109]
	v_pk_fma_f32 v[72:73], v[22:23], v[110:111], v[72:73]
	v_pk_fma_f32 v[140:141], v[138:139], v[116:117], v[20:21] op_sel:[1,0,0] op_sel_hi:[1,1,1]
	v_add_f32_e32 v74, v72, v73
	v_pk_fma_f32 v[142:143], v[138:139], v[118:119], v[22:23] op_sel:[1,0,0] op_sel_hi:[1,1,1]
	v_pk_mul_f32 v[198:199], v[20:21], v[104:105]
	v_add_f32_dpp v74, v74, v74 quad_perm:[1,0,3,2] row_mask:0xf bank_mask:0xf bound_ctrl:1
	v_pk_fma_f32 v[198:199], v[22:23], v[106:107], v[198:199]
	v_add_f32_e32 v154, v198, v199
	v_add_f32_dpp v74, v74, v74 quad_perm:[2,3,0,1] row_mask:0xf bank_mask:0xf bound_ctrl:1
	ds_read_b128 v[92:95], v70 offset:11520
	ds_read_b128 v[100:103], v70 offset:27904
	v_add_f32_dpp v74, v74, v74 row_half_mirror row_mask:0xf bank_mask:0xf bound_ctrl:1
	ds_read_b128 v[96:99], v70 offset:19712
	ds_read_b128 v[104:107], v70 offset:36096
	v_add_f32_dpp v74, v74, v74 row_mirror row_mask:0xf bank_mask:0xf bound_ctrl:1
	v_pk_fma_f32 v[20:21], v[112:113], v[74:75], v[140:141] op_sel_hi:[1,0,1] neg_lo:[0,1,0] neg_hi:[0,1,0]
	v_pk_fma_f32 v[22:23], v[114:115], v[74:75], v[142:143] op_sel_hi:[1,0,1] neg_lo:[0,1,0] neg_hi:[0,1,0]
	v_pk_mul_f32 v[12:13], v[20:21], v[28:29]
	v_pk_mul_f32 v[14:15], v[22:23], v[30:31]
	v_add_f32_dpp v178, v146, v146 row_mirror row_mask:0xf bank_mask:0x3
	s_nop 1
	v_add_f32_dpp v178, v154, v154 row_mirror row_mask:0xf bank_mask:0xc
	s_waitcnt lgkmcnt(4)
	v_pk_mul_f32 v[72:73], v[12:13], v[76:77]
	v_pk_fma_f32 v[72:73], v[14:15], v[78:79], v[72:73]
	v_pk_fma_f32 v[140:141], v[136:137], v[84:85], v[12:13] op_sel_hi:[0,1,1]
	v_add_f32_e32 v74, v72, v73
	v_pk_fma_f32 v[142:143], v[136:137], v[86:87], v[14:15] op_sel_hi:[0,1,1]
	v_pk_mul_f32 v[198:199], v[20:21], v[120:121]
	v_add_f32_dpp v74, v74, v74 quad_perm:[1,0,3,2] row_mask:0xf bank_mask:0xf bound_ctrl:1
	v_pk_fma_f32 v[198:199], v[22:23], v[122:123], v[198:199]
	v_add_f32_e32 v155, v198, v199
	v_add_f32_dpp v74, v74, v74 quad_perm:[2,3,0,1] row_mask:0xf bank_mask:0xf bound_ctrl:1
	ds_read_b128 v[108:111], v70 offset:11776
	ds_read_b128 v[116:119], v70 offset:28160
	v_add_f32_dpp v74, v74, v74 row_half_mirror row_mask:0xf bank_mask:0xf bound_ctrl:1
	ds_read_b128 v[112:115], v70 offset:19968
	ds_read_b128 v[120:123], v70 offset:36352
	v_add_f32_dpp v74, v74, v74 row_mirror row_mask:0xf bank_mask:0xf bound_ctrl:1
	v_pk_fma_f32 v[12:13], v[80:81], v[74:75], v[140:141] op_sel_hi:[1,0,1] neg_lo:[0,1,0] neg_hi:[0,1,0]
	v_pk_fma_f32 v[14:15], v[82:83], v[74:75], v[142:143] op_sel_hi:[1,0,1] neg_lo:[0,1,0] neg_hi:[0,1,0]
	ds_read_b128 v[28:31], v70 offset:3584
	ds_read2_b32 v[138:139], v71 offset0:224 offset1:240
	v_add_f32_dpp v179, v147, v147 row_mirror row_mask:0xf bank_mask:0x3
	s_nop 1
	v_add_f32_dpp v179, v155, v155 row_mirror row_mask:0xf bank_mask:0xc
	s_waitcnt lgkmcnt(6)
	v_pk_mul_f32 v[72:73], v[12:13], v[92:93]
	v_pk_fma_f32 v[72:73], v[14:15], v[94:95], v[72:73]
	v_pk_fma_f32 v[140:141], v[136:137], v[100:101], v[12:13] op_sel:[1,0,0] op_sel_hi:[1,1,1]
	v_add_f32_e32 v74, v72, v73
	v_pk_fma_f32 v[142:143], v[136:137], v[102:103], v[14:15] op_sel:[1,0,0] op_sel_hi:[1,1,1]
	v_pk_mul_f32 v[198:199], v[12:13], v[88:89]
	v_add_f32_dpp v74, v74, v74 quad_perm:[1,0,3,2] row_mask:0xf bank_mask:0xf bound_ctrl:1
	v_pk_fma_f32 v[198:199], v[14:15], v[90:91], v[198:199]
	v_add_f32_e32 v156, v198, v199
	v_add_f32_dpp v74, v74, v74 quad_perm:[2,3,0,1] row_mask:0xf bank_mask:0xf bound_ctrl:1
	ds_read_b128 v[76:79], v70 offset:12032
	ds_read_b128 v[84:87], v70 offset:28416
	v_add_f32_dpp v74, v74, v74 row_half_mirror row_mask:0xf bank_mask:0xf bound_ctrl:1
	ds_read_b128 v[80:83], v70 offset:20224
	ds_read_b128 v[88:91], v70 offset:36608
	v_add_f32_dpp v74, v74, v74 row_mirror row_mask:0xf bank_mask:0xf bound_ctrl:1
	v_pk_fma_f32 v[12:13], v[96:97], v[74:75], v[140:141] op_sel_hi:[1,0,1] neg_lo:[0,1,0] neg_hi:[0,1,0]
	v_pk_fma_f32 v[14:15], v[98:99], v[74:75], v[142:143] op_sel_hi:[1,0,1] neg_lo:[0,1,0] neg_hi:[0,1,0]
	v_pk_mul_f32 v[20:21], v[12:13], v[24:25]
	v_pk_mul_f32 v[22:23], v[14:15], v[26:27]
	v_add_f32_dpp v180, v148, v148 row_mirror row_mask:0xf bank_mask:0x3
	s_nop 1
	v_add_f32_dpp v180, v156, v156 row_mirror row_mask:0xf bank_mask:0xc
	s_waitcnt lgkmcnt(4)
	v_pk_mul_f32 v[72:73], v[20:21], v[108:109]
	v_pk_fma_f32 v[72:73], v[22:23], v[110:111], v[72:73]
	v_pk_fma_f32 v[140:141], v[138:139], v[116:117], v[20:21] op_sel_hi:[0,1,1]
	v_add_f32_e32 v74, v72, v73
	v_pk_fma_f32 v[142:143], v[138:139], v[118:119], v[22:23] op_sel_hi:[0,1,1]
	v_pk_mul_f32 v[198:199], v[12:13], v[104:105]
	v_add_f32_dpp v74, v74, v74 quad_perm:[1,0,3,2] row_mask:0xf bank_mask:0xf bound_ctrl:1
	v_pk_fma_f32 v[198:199], v[14:15], v[106:107], v[198:199]
	v_add_f32_e32 v157, v198, v199
	v_add_f32_dpp v74, v74, v74 quad_perm:[2,3,0,1] row_mask:0xf bank_mask:0xf bound_ctrl:1
	ds_read_b128 v[92:95], v70 offset:12288
	ds_read_b128 v[100:103], v70 offset:28672
	v_add_f32_dpp v74, v74, v74 row_half_mirror row_mask:0xf bank_mask:0xf bound_ctrl:1
	ds_read_b128 v[96:99], v70 offset:20480
	ds_read_b128 v[104:107], v70 offset:36864
	v_add_f32_dpp v74, v74, v74 row_mirror row_mask:0xf bank_mask:0xf bound_ctrl:1
	v_pk_fma_f32 v[20:21], v[112:113], v[74:75], v[140:141] op_sel_hi:[1,0,1] neg_lo:[0,1,0] neg_hi:[0,1,0]
	v_pk_fma_f32 v[22:23], v[114:115], v[74:75], v[142:143] op_sel_hi:[1,0,1] neg_lo:[0,1,0] neg_hi:[0,1,0]
	ds_read_b128 v[24:27], v70 offset:4096
	ds_read2_b32 v[136:137], v2 offset0:0 offset1:16
	v_add_f32_dpp v184, v176, v176 row_half_mirror row_mask:0xf bank_mask:0x5
	s_nop 1
	v_add_f32_dpp v184, v180, v180 row_half_mirror row_mask:0xf bank_mask:0xa
	s_waitcnt lgkmcnt(6)
; #define RW_LD(X, s) do { X.d = *(const LAS f32x4*)(bs + (s) * 256); X.k = *(const LAS f32x4*)(bs + 8192 + (s) * 256); X.a = *(const LAS f32x4*)(bs + 16384 + (s) * 256); \
;                          X.p = *(const LAS f32x4*)(bs + 24576 + (s) * 256); X.r = *(const LAS f32x4*)(bs + 32768 + (s) * 256); X.v = *(const LAS float*)(bv + (s) * 64); } while (0)
; #define RW_STEP(X, s) do { float sa = fmaf(S[3], X.k[3], fmaf(S[2], X.k[2], fmaf(S[1], X.k[1], S[0] * X.k[0]))); const f32x4 T = S * X.d + X.v * X.p; sa = -red16(sa); \
;                            S = T + sa * X.a; float y = fmaf(S[3], X.r[3], fmaf(S[2], X.r[2], fmaf(S[1], X.r[1], S[0] * X.r[0]))); y = red16(y); \
;                            yk = fmaf(selv[(s) & 15], y, yk); } while (0)
; #define RW_YST(s) do { if ((s) == 15) { ob[(size_t)(rowbase + c * 32 + seg) * D + 512 + h * 64 + vrow] = f2bf(yk); yk = 0.f; } } while (0)
; __device__ __forceinline__ void rwkv_scan(const Params& p, LAS unsigned char* lds, int rowbase, int T, int h, int q4, const float* S0, float* Sout) {
;     ...
;             RwStep xa, xb, xc; float yk = 0.f;
;     ...
;             RW_LD(xa, 0); RW_LD(xb, 1);
; #pragma unroll
;             for (int s = 0; s < 30; s += 3) {
;                 RW_LD(xc, s + 2); RW_STEP(xa, s); RW_YST(s);
;                 RW_LD(xa, s + 3); RW_STEP(xb, s + 1); RW_YST(s + 1);
;                 RW_LD(xb, s + 4); RW_STEP(xc, s + 2); RW_YST(s + 2);
;             }
	v_pk_mul_f32 v[72:73], v[20:21], v[76:77]
	v_pk_fma_f32 v[72:73], v[22:23], v[78:79], v[72:73]
	v_pk_fma_f32 v[140:141], v[138:139], v[84:85], v[20:21] op_sel:[1,0,0] op_sel_hi:[1,1,1]
	v_add_f32_e32 v74, v72, v73
	v_pk_fma_f32 v[142:143], v[138:139], v[86:87], v[22:23] op_sel:[1,0,0] op_sel_hi:[1,1,1]
	v_pk_mul_f32 v[198:199], v[20:21], v[120:121]
	v_add_f32_dpp v74, v74, v74 quad_perm:[1,0,3,2] row_mask:0xf bank_mask:0xf bound_ctrl:1
	v_pk_fma_f32 v[198:199], v[22:23], v[122:123], v[198:199]
	v_add_f32_e32 v158, v198, v199
	v_add_f32_dpp v74, v74, v74 quad_perm:[2,3,0,1] row_mask:0xf bank_mask:0xf bound_ctrl:1
	ds_read_b128 v[108:111], v70 offset:12544
	ds_read_b128 v[116:119], v70 offset:28928
	v_add_f32_dpp v74, v74, v74 row_half_mirror row_mask:0xf bank_mask:0xf bound_ctrl:1
	ds_read_b128 v[112:115], v70 offset:20736
	ds_read_b128 v[120:123], v70 offset:37120
	v_add_f32_dpp v74, v74, v74 row_mirror row_mask:0xf bank_mask:0xf bound_ctrl:1
	v_pk_fma_f32 v[20:21], v[80:81], v[74:75], v[140:141] op_sel_hi:[1,0,1] neg_lo:[0,1,0] neg_hi:[0,1,0]
	v_pk_fma_f32 v[22:23], v[82:83], v[74:75], v[142:143] op_sel_hi:[1,0,1] neg_lo:[0,1,0] neg_hi:[0,1,0]
	v_pk_mul_f32 v[12:13], v[20:21], v[28:29]
	v_pk_mul_f32 v[14:15], v[22:23], v[30:31]
	v_add_f32_dpp v181, v149, v149 row_mirror row_mask:0xf bank_mask:0x3
	s_nop 1
	v_add_f32_dpp v181, v157, v157 row_mirror row_mask:0xf bank_mask:0xc
	v_add_f32_dpp v185, v177, v177 row_half_mirror row_mask:0xf bank_mask:0x5
	s_waitcnt lgkmcnt(4)
	v_pk_mul_f32 v[72:73], v[12:13], v[92:93]
	v_pk_fma_f32 v[72:73], v[14:15], v[94:95], v[72:73]
	v_pk_fma_f32 v[140:141], v[136:137], v[100:101], v[12:13] op_sel_hi:[0,1,1]
	v_add_f32_e32 v74, v72, v73
	v_pk_fma_f32 v[142:143], v[136:137], v[102:103], v[14:15] op_sel_hi:[0,1,1]
	v_pk_mul_f32 v[198:199], v[20:21], v[88:89]
	v_add_f32_dpp v74, v74, v74 quad_perm:[1,0,3,2] row_mask:0xf bank_mask:0xf bound_ctrl:1
	v_pk_fma_f32 v[198:199], v[22:23], v[90:91], v[198:199]
	v_add_f32_e32 v159, v198, v199
	v_add_f32_dpp v74, v74, v74 quad_perm:[2,3,0,1] row_mask:0xf bank_mask:0xf bound_ctrl:1
	ds_read_b128 v[76:79], v70 offset:12800
	ds_read_b128 v[84:87], v70 offset:29184
	v_add_f32_dpp v74, v74, v74 row_half_mirror row_mask:0xf bank_mask:0xf bound_ctrl:1
	ds_read_b128 v[80:83], v70 offset:20992
	ds_read_b128 v[88:91], v70 offset:37376
	v_add_f32_dpp v74, v74, v74 row_mirror row_mask:0xf bank_mask:0xf bound_ctrl:1
	v_pk_fma_f32 v[12:13], v[96:97], v[74:75], v[140:141] op_sel_hi:[1,0,1] neg_lo:[0,1,0] neg_hi:[0,1,0]
	v_pk_fma_f32 v[14:15], v[98:99], v[74:75], v[142:143] op_sel_hi:[1,0,1] neg_lo:[0,1,0] neg_hi:[0,1,0]
	ds_read_b128 v[28:31], v70 offset:4608
	ds_read2_b32 v[138:139], v2 offset0:32 offset1:48
	v_add_f32_dpp v185, v181, v181 row_half_mirror row_mask:0xf bank_mask:0xa
	v_add_f32_dpp v182, v150, v150 row_mirror row_mask:0xf bank_mask:0x3
	s_nop 1
	v_add_f32_dpp v182, v158, v158 row_mirror row_mask:0xf bank_mask:0xc
	s_waitcnt lgkmcnt(6)
	v_pk_mul_f32 v[72:73], v[12:13], v[108:109]
	v_pk_fma_f32 v[72:73], v[14:15], v[110:111], v[72:73]
	v_pk_fma_f32 v[140:141], v[136:137], v[116:117], v[12:13] op_sel:[1,0,0] op_sel_hi:[1,1,1]
	v_add_f32_e32 v74, v72, v73
	v_pk_fma_f32 v[142:143], v[136:137], v[118:119], v[14:15] op_sel:[1,0,0] op_sel_hi:[1,1,1]
	v_pk_mul_f32 v[198:199], v[12:13], v[104:105]
	v_add_f32_dpp v74, v74, v74 quad_perm:[1,0,3,2] row_mask:0xf bank_mask:0xf bound_ctrl:1
	v_pk_fma_f32 v[198:199], v[14:15], v[106:107], v[198:199]
	v_add_f32_e32 v160, v198, v199
	v_add_f32_dpp v74, v74, v74 quad_perm:[2,3,0,1] row_mask:0xf bank_mask:0xf bound_ctrl:1
	ds_read_b128 v[92:95], v70 offset:13056
	ds_read_b128 v[100:103], v70 offset:29440
	v_add_f32_dpp v74, v74, v74 row_half_mirror row_mask:0xf bank_mask:0xf bound_ctrl:1
	ds_read_b128 v[96:99], v70 offset:21248
	ds_read_b128 v[104:107], v70 offset:37632
	v_add_f32_dpp v74, v74, v74 row_mirror row_mask:0xf bank_mask:0xf bound_ctrl:1
	v_pk_fma_f32 v[12:13], v[112:113], v[74:75], v[140:141] op_sel_hi:[1,0,1] neg_lo:[0,1,0] neg_hi:[0,1,0]
	v_pk_fma_f32 v[14:15], v[114:115], v[74:75], v[142:143] op_sel_hi:[1,0,1] neg_lo:[0,1,0] neg_hi:[0,1,0]
	v_pk_mul_f32 v[20:21], v[12:13], v[24:25]
	v_pk_mul_f32 v[22:23], v[14:15], v[26:27]
	v_add_f32_dpp v186, v178, v178 row_half_mirror row_mask:0xf bank_mask:0x5
	s_nop 1
	v_add_f32_dpp v186, v182, v182 row_half_mirror row_mask:0xf bank_mask:0xa
	v_cndmask_b32_e64 v190, v184, v186, s[98:99]
	s_waitcnt lgkmcnt(4)
	v_pk_mul_f32 v[72:73], v[20:21], v[76:77]
	v_pk_fma_f32 v[72:73], v[22:23], v[78:79], v[72:73]
	v_pk_fma_f32 v[140:141], v[138:139], v[84:85], v[20:21] op_sel_hi:[0,1,1]
	v_add_f32_e32 v74, v72, v73
	v_pk_fma_f32 v[142:143], v[138:139], v[86:87], v[22:23] op_sel_hi:[0,1,1]
	v_pk_mul_f32 v[198:199], v[12:13], v[120:121]
	v_add_f32_dpp v74, v74, v74 quad_perm:[1,0,3,2] row_mask:0xf bank_mask:0xf bound_ctrl:1
	v_pk_fma_f32 v[198:199], v[14:15], v[122:123], v[198:199]
	v_add_f32_e32 v161, v198, v199
	v_add_f32_dpp v74, v74, v74 quad_perm:[2,3,0,1] row_mask:0xf bank_mask:0xf bound_ctrl:1
	ds_read_b128 v[108:111], v70 offset:13312
	ds_read_b128 v[116:119], v70 offset:29696
	v_add_f32_dpp v74, v74, v74 row_half_mirror row_mask:0xf bank_mask:0xf bound_ctrl:1
	ds_read_b128 v[112:115], v70 offset:21504
	ds_read_b128 v[120:123], v70 offset:37888
	v_add_f32_dpp v74, v74, v74 row_mirror row_mask:0xf bank_mask:0xf bound_ctrl:1
	v_pk_fma_f32 v[20:21], v[80:81], v[74:75], v[140:141] op_sel_hi:[1,0,1] neg_lo:[0,1,0] neg_hi:[0,1,0]
	v_pk_fma_f32 v[22:23], v[82:83], v[74:75], v[142:143] op_sel_hi:[1,0,1] neg_lo:[0,1,0] neg_hi:[0,1,0]
	ds_read_b128 v[24:27], v70 offset:5120
	ds_read2_b32 v[136:137], v2 offset0:64 offset1:80
	v_cndmask_b32_e64 v191, v186, v184, s[98:99]
	s_nop 1
	v_add_f32_dpp v188, v191, v190 quad_perm:[2,3,0,1] row_mask:0xf bank_mask:0xf
	v_add_f32_dpp v183, v151, v151 row_mirror row_mask:0xf bank_mask:0x3
	s_waitcnt lgkmcnt(6)
; #define RW_LD(X, s) do { X.d = *(const LAS f32x4*)(bs + (s) * 256); X.k = *(const LAS f32x4*)(bs + 8192 + (s) * 256); X.a = *(const LAS f32x4*)(bs + 16384 + (s) * 256); \
;                          X.p = *(const LAS f32x4*)(bs + 24576 + (s) * 256); X.r = *(const LAS f32x4*)(bs + 32768 + (s) * 256); X.v = *(const LAS float*)(bv + (s) * 64); } while (0)
; #define RW_STEP(X, s) do { float sa = fmaf(S[3], X.k[3], fmaf(S[2], X.k[2], fmaf(S[1], X.k[1], S[0] * X.k[0]))); const f32x4 T = S * X.d + X.v * X.p; sa = -red16(sa); \
;                            S = T + sa * X.a; float y = fmaf(S[3], X.r[3], fmaf(S[2], X.r[2], fmaf(S[1], X.r[1], S[0] * X.r[0]))); y = red16(y); \
;                            yk = fmaf(selv[(s) & 15], y, yk); } while (0)
; #define RW_YST(s) do { if ((s) == 15) { ob[(size_t)(rowbase + c * 32 + seg) * D + 512 + h * 64 + vrow] = f2bf(yk); yk = 0.f; } } while (0)
; __device__ __forceinline__ void rwkv_scan(const Params& p, LAS unsigned char* lds, int rowbase, int T, int h, int q4, const float* S0, float* Sout) {
;     ...
;             RwStep xa, xb, xc; float yk = 0.f;
;     ...
;             RW_LD(xa, 0); RW_LD(xb, 1);
; #pragma unroll
;             for (int s = 0; s < 30; s += 3) {
;                 RW_LD(xc, s + 2); RW_STEP(xa, s); RW_YST(s);
;                 RW_LD(xa, s + 3); RW_STEP(xb, s + 1); RW_YST(s + 1);
;                 RW_LD(xb, s + 4); RW_STEP(xc, s + 2); RW_YST(s + 2);
;             }
	v_pk_mul_f32 v[72:73], v[20:21], v[92:93]
	v_pk_fma_f32 v[72:73], v[22:23], v[94:95], v[72:73]
	v_pk_fma_f32 v[140:141], v[138:139], v[100:101], v[20:21] op_sel:[1,0,0] op_sel_hi:[1,1,1]
	v_add_f32_e32 v74, v72, v73
	v_pk_fma_f32 v[142:143], v[138:139], v[102:103], v[22:23] op_sel:[1,0,0] op_sel_hi:[1,1,1]
	v_pk_mul_f32 v[198:199], v[20:21], v[88:89]
	v_add_f32_dpp v74, v74, v74 quad_perm:[1,0,3,2] row_mask:0xf bank_mask:0xf bound_ctrl:1
	v_pk_fma_f32 v[198:199], v[22:23], v[90:91], v[198:199]
	v_add_f32_e32 v162, v198, v199
	v_add_f32_dpp v74, v74, v74 quad_perm:[2,3,0,1] row_mask:0xf bank_mask:0xf bound_ctrl:1
	ds_read_b128 v[76:79], v70 offset:13568
	ds_read_b128 v[84:87], v70 offset:29952
	v_add_f32_dpp v74, v74, v74 row_half_mirror row_mask:0xf bank_mask:0xf bound_ctrl:1
	ds_read_b128 v[80:83], v70 offset:21760
	ds_read_b128 v[88:91], v70 offset:38144
	v_add_f32_dpp v74, v74, v74 row_mirror row_mask:0xf bank_mask:0xf bound_ctrl:1
	v_pk_fma_f32 v[20:21], v[96:97], v[74:75], v[140:141] op_sel_hi:[1,0,1] neg_lo:[0,1,0] neg_hi:[0,1,0]
	v_pk_fma_f32 v[22:23], v[98:99], v[74:75], v[142:143] op_sel_hi:[1,0,1] neg_lo:[0,1,0] neg_hi:[0,1,0]
	v_pk_mul_f32 v[12:13], v[20:21], v[28:29]
	v_pk_mul_f32 v[14:15], v[22:23], v[30:31]
	v_add_f32_dpp v183, v159, v159 row_mirror row_mask:0xf bank_mask:0xc
	v_add_f32_dpp v187, v179, v179 row_half_mirror row_mask:0xf bank_mask:0x5
	s_nop 1
	v_add_f32_dpp v187, v183, v183 row_half_mirror row_mask:0xf bank_mask:0xa
	s_waitcnt lgkmcnt(4)
	v_pk_mul_f32 v[72:73], v[12:13], v[108:109]
	v_pk_fma_f32 v[72:73], v[14:15], v[110:111], v[72:73]
	v_pk_fma_f32 v[140:141], v[136:137], v[116:117], v[12:13] op_sel_hi:[0,1,1]
	v_add_f32_e32 v74, v72, v73
	v_pk_fma_f32 v[142:143], v[136:137], v[118:119], v[14:15] op_sel_hi:[0,1,1]
	v_pk_mul_f32 v[198:199], v[20:21], v[104:105]
	v_add_f32_dpp v74, v74, v74 quad_perm:[1,0,3,2] row_mask:0xf bank_mask:0xf bound_ctrl:1
	v_pk_fma_f32 v[198:199], v[22:23], v[106:107], v[198:199]
	v_add_f32_e32 v163, v198, v199
	v_add_f32_dpp v74, v74, v74 quad_perm:[2,3,0,1] row_mask:0xf bank_mask:0xf bound_ctrl:1
	ds_read_b128 v[92:95], v70 offset:13824
	ds_read_b128 v[100:103], v70 offset:30208
	v_add_f32_dpp v74, v74, v74 row_half_mirror row_mask:0xf bank_mask:0xf bound_ctrl:1
	ds_read_b128 v[96:99], v70 offset:22016
	ds_read_b128 v[104:107], v70 offset:38400
	v_add_f32_dpp v74, v74, v74 row_mirror row_mask:0xf bank_mask:0xf bound_ctrl:1
	v_pk_fma_f32 v[12:13], v[112:113], v[74:75], v[140:141] op_sel_hi:[1,0,1] neg_lo:[0,1,0] neg_hi:[0,1,0]
	v_pk_fma_f32 v[14:15], v[114:115], v[74:75], v[142:143] op_sel_hi:[1,0,1] neg_lo:[0,1,0] neg_hi:[0,1,0]
	ds_read_b128 v[28:31], v70 offset:5632
	ds_read2_b32 v[138:139], v2 offset0:96 offset1:112
	v_cndmask_b32_e64 v190, v185, v187, s[98:99]
	v_cndmask_b32_e64 v191, v187, v185, s[98:99]
	s_nop 1
	v_add_f32_dpp v189, v191, v190 quad_perm:[2,3,0,1] row_mask:0xf bank_mask:0xf
	s_waitcnt lgkmcnt(6)
	v_pk_mul_f32 v[72:73], v[12:13], v[76:77]
	v_pk_fma_f32 v[72:73], v[14:15], v[78:79], v[72:73]
	v_pk_fma_f32 v[140:141], v[136:137], v[84:85], v[12:13] op_sel:[1,0,0] op_sel_hi:[1,1,1]
	v_add_f32_e32 v74, v72, v73
	v_pk_fma_f32 v[142:143], v[136:137], v[86:87], v[14:15] op_sel:[1,0,0] op_sel_hi:[1,1,1]
	v_pk_mul_f32 v[198:199], v[12:13], v[120:121]
	v_add_f32_dpp v74, v74, v74 quad_perm:[1,0,3,2] row_mask:0xf bank_mask:0xf bound_ctrl:1
	v_pk_fma_f32 v[198:199], v[14:15], v[122:123], v[198:199]
	v_add_f32_e32 v164, v198, v199
	v_add_f32_dpp v74, v74, v74 quad_perm:[2,3,0,1] row_mask:0xf bank_mask:0xf bound_ctrl:1
	ds_read_b128 v[108:111], v70 offset:14080
	ds_read_b128 v[116:119], v70 offset:30464
	v_add_f32_dpp v74, v74, v74 row_half_mirror row_mask:0xf bank_mask:0xf bound_ctrl:1
	ds_read_b128 v[112:115], v70 offset:22272
	ds_read_b128 v[120:123], v70 offset:38656
	v_add_f32_dpp v74, v74, v74 row_mirror row_mask:0xf bank_mask:0xf bound_ctrl:1
	v_pk_fma_f32 v[12:13], v[80:81], v[74:75], v[140:141] op_sel_hi:[1,0,1] neg_lo:[0,1,0] neg_hi:[0,1,0]
	v_pk_fma_f32 v[14:15], v[82:83], v[74:75], v[142:143] op_sel_hi:[1,0,1] neg_lo:[0,1,0] neg_hi:[0,1,0]
	v_pk_mul_f32 v[20:21], v[12:13], v[24:25]
	v_pk_mul_f32 v[22:23], v[14:15], v[26:27]
	v_cndmask_b32_e64 v190, v188, v189, s[100:101]
	v_cndmask_b32_e64 v191, v189, v188, s[100:101]
	s_nop 1
	v_add_f32_dpp v192, v191, v190 quad_perm:[1,0,3,2] row_mask:0xf bank_mask:0xf
	s_waitcnt lgkmcnt(4)
	v_pk_mul_f32 v[72:73], v[20:21], v[92:93]
	v_pk_fma_f32 v[72:73], v[22:23], v[94:95], v[72:73]
	v_pk_fma_f32 v[140:141], v[138:139], v[100:101], v[20:21] op_sel_hi:[0,1,1]
	v_add_f32_e32 v74, v72, v73
	v_pk_fma_f32 v[142:143], v[138:139], v[102:103], v[22:23] op_sel_hi:[0,1,1]
	v_pk_mul_f32 v[198:199], v[12:13], v[88:89]
	v_add_f32_dpp v74, v74, v74 quad_perm:[1,0,3,2] row_mask:0xf bank_mask:0xf bound_ctrl:1
	v_pk_fma_f32 v[198:199], v[14:15], v[90:91], v[198:199]
	v_add_f32_e32 v165, v198, v199
	v_add_f32_dpp v74, v74, v74 quad_perm:[2,3,0,1] row_mask:0xf bank_mask:0xf bound_ctrl:1
	ds_read_b128 v[76:79], v70 offset:14336
	ds_read_b128 v[84:87], v70 offset:30720
	v_add_f32_dpp v74, v74, v74 row_half_mirror row_mask:0xf bank_mask:0xf bound_ctrl:1
	ds_read_b128 v[80:83], v70 offset:22528
	ds_read_b128 v[88:91], v70 offset:38912
	v_add_f32_dpp v74, v74, v74 row_mirror row_mask:0xf bank_mask:0xf bound_ctrl:1
	v_pk_fma_f32 v[20:21], v[96:97], v[74:75], v[140:141] op_sel_hi:[1,0,1] neg_lo:[0,1,0] neg_hi:[0,1,0]
	v_pk_fma_f32 v[22:23], v[98:99], v[74:75], v[142:143] op_sel_hi:[1,0,1] neg_lo:[0,1,0] neg_hi:[0,1,0]
	ds_read_b128 v[24:27], v70 offset:6144
	ds_read2_b32 v[136:137], v2 offset0:128 offset1:144
	v_lshlrev_b32_e32 v194, 11, v196
	v_mov_b32_e32 v195, 0
	s_waitcnt lgkmcnt(6)
; #define RW_LD(X, s) do { X.d = *(const LAS f32x4*)(bs + (s) * 256); X.k = *(const LAS f32x4*)(bs + 8192 + (s) * 256); X.a = *(const LAS f32x4*)(bs + 16384 + (s) * 256); \
;                          X.p = *(const LAS f32x4*)(bs + 24576 + (s) * 256); X.r = *(const LAS f32x4*)(bs + 32768 + (s) * 256); X.v = *(const LAS float*)(bv + (s) * 64); } while (0)
; #define RW_STEP(X, s) do { float sa = fmaf(S[3], X.k[3], fmaf(S[2], X.k[2], fmaf(S[1], X.k[1], S[0] * X.k[0]))); const f32x4 T = S * X.d + X.v * X.p; sa = -red16(sa); \
;                            S = T + sa * X.a; float y = fmaf(S[3], X.r[3], fmaf(S[2], X.r[2], fmaf(S[1], X.r[1], S[0] * X.r[0]))); y = red16(y); \
;                            yk = fmaf(selv[(s) & 15], y, yk); } while (0)
; #define RW_YST(s) do { if ((s) == 15) { ob[(size_t)(rowbase + c * 32 + seg) * D + 512 + h * 64 + vrow] = f2bf(yk); yk = 0.f; } } while (0)
; __device__ __forceinline__ void rwkv_scan(const Params& p, LAS unsigned char* lds, int rowbase, int T, int h, int q4, const float* S0, float* Sout) {
;     ...
;             RwStep xa, xb, xc; float yk = 0.f;
;     ...
;             RW_LD(xa, 0); RW_LD(xb, 1);
; #pragma unroll
;             for (int s = 0; s < 30; s += 3) {
;                 RW_LD(xc, s + 2); RW_STEP(xa, s); RW_YST(s);
;                 RW_LD(xa, s + 3); RW_STEP(xb, s + 1); RW_YST(s + 1);
;                 RW_LD(xb, s + 4); RW_STEP(xc, s + 2); RW_YST(s + 2);
;             }
	v_pk_mul_f32 v[72:73], v[20:21], v[108:109]
	v_pk_fma_f32 v[72:73], v[22:23], v[110:111], v[72:73]
	v_pk_fma_f32 v[140:141], v[138:139], v[116:117], v[20:21] op_sel:[1,0,0] op_sel_hi:[1,1,1]
	v_add_f32_e32 v74, v72, v73
	v_pk_fma_f32 v[142:143], v[138:139], v[118:119], v[22:23] op_sel:[1,0,0] op_sel_hi:[1,1,1]
	v_pk_mul_f32 v[198:199], v[20:21], v[104:105]
	v_add_f32_dpp v74, v74, v74 quad_perm:[1,0,3,2] row_mask:0xf bank_mask:0xf bound_ctrl:1
	v_pk_fma_f32 v[198:199], v[22:23], v[106:107], v[198:199]
	v_add_f32_e32 v166, v198, v199
	v_add_f32_dpp v74, v74, v74 quad_perm:[2,3,0,1] row_mask:0xf bank_mask:0xf bound_ctrl:1
	ds_read_b128 v[92:95], v70 offset:14592
	ds_read_b128 v[100:103], v70 offset:30976
	v_add_f32_dpp v74, v74, v74 row_half_mirror row_mask:0xf bank_mask:0xf bound_ctrl:1
	ds_read_b128 v[96:99], v70 offset:22784
	ds_read_b128 v[104:107], v70 offset:39168
	v_add_f32_dpp v74, v74, v74 row_mirror row_mask:0xf bank_mask:0xf bound_ctrl:1
	v_pk_fma_f32 v[20:21], v[112:113], v[74:75], v[140:141] op_sel_hi:[1,0,1] neg_lo:[0,1,0] neg_hi:[0,1,0]
	v_pk_fma_f32 v[22:23], v[114:115], v[74:75], v[142:143] op_sel_hi:[1,0,1] neg_lo:[0,1,0] neg_hi:[0,1,0]
	v_pk_mul_f32 v[12:13], v[20:21], v[28:29]
	v_pk_mul_f32 v[14:15], v[22:23], v[30:31]
	v_cvt_pk_bf16_f32 v193, v192, v192
	v_lshl_add_u64 v[194:195], v[42:43], 0, v[194:195]
	s_waitcnt lgkmcnt(4)
	v_pk_mul_f32 v[72:73], v[12:13], v[76:77]
	v_pk_fma_f32 v[72:73], v[14:15], v[78:79], v[72:73]
	v_pk_fma_f32 v[140:141], v[136:137], v[84:85], v[12:13] op_sel_hi:[0,1,1]
	v_add_f32_e32 v74, v72, v73
	v_pk_fma_f32 v[142:143], v[136:137], v[86:87], v[14:15] op_sel_hi:[0,1,1]
	v_pk_mul_f32 v[198:199], v[20:21], v[120:121]
	v_add_f32_dpp v74, v74, v74 quad_perm:[1,0,3,2] row_mask:0xf bank_mask:0xf bound_ctrl:1
	v_pk_fma_f32 v[198:199], v[22:23], v[122:123], v[198:199]
	v_add_f32_e32 v167, v198, v199
	v_add_f32_dpp v74, v74, v74 quad_perm:[2,3,0,1] row_mask:0xf bank_mask:0xf bound_ctrl:1
	ds_read_b128 v[108:111], v70 offset:14848
	ds_read_b128 v[116:119], v70 offset:31232
	v_add_f32_dpp v74, v74, v74 row_half_mirror row_mask:0xf bank_mask:0xf bound_ctrl:1
	ds_read_b128 v[112:115], v70 offset:23040
	ds_read_b128 v[120:123], v70 offset:39424
	v_add_f32_dpp v74, v74, v74 row_mirror row_mask:0xf bank_mask:0xf bound_ctrl:1
	v_pk_fma_f32 v[12:13], v[80:81], v[74:75], v[140:141] op_sel_hi:[1,0,1] neg_lo:[0,1,0] neg_hi:[0,1,0]
	v_pk_fma_f32 v[14:15], v[82:83], v[74:75], v[142:143] op_sel_hi:[1,0,1] neg_lo:[0,1,0] neg_hi:[0,1,0]
	ds_read_b128 v[28:31], v70 offset:6656
	ds_read2_b32 v[138:139], v2 offset0:160 offset1:176
	global_store_short v[194:195], v193, off offset:1024
	s_waitcnt lgkmcnt(6)
	v_pk_mul_f32 v[72:73], v[12:13], v[92:93]
	v_pk_fma_f32 v[72:73], v[14:15], v[94:95], v[72:73]
	v_pk_fma_f32 v[140:141], v[136:137], v[100:101], v[12:13] op_sel:[1,0,0] op_sel_hi:[1,1,1]
	v_add_f32_e32 v74, v72, v73
	v_pk_fma_f32 v[142:143], v[136:137], v[102:103], v[14:15] op_sel:[1,0,0] op_sel_hi:[1,1,1]
	v_pk_mul_f32 v[198:199], v[12:13], v[88:89]
	v_add_f32_dpp v74, v74, v74 quad_perm:[1,0,3,2] row_mask:0xf bank_mask:0xf bound_ctrl:1
	v_pk_fma_f32 v[198:199], v[14:15], v[90:91], v[198:199]
	v_add_f32_e32 v168, v198, v199
	v_add_f32_dpp v74, v74, v74 quad_perm:[2,3,0,1] row_mask:0xf bank_mask:0xf bound_ctrl:1
	ds_read_b128 v[76:79], v70 offset:15104
	ds_read_b128 v[84:87], v70 offset:31488
	v_add_f32_dpp v74, v74, v74 row_half_mirror row_mask:0xf bank_mask:0xf bound_ctrl:1
	ds_read_b128 v[80:83], v70 offset:23296
	ds_read_b128 v[88:91], v70 offset:39680
	v_add_f32_dpp v74, v74, v74 row_mirror row_mask:0xf bank_mask:0xf bound_ctrl:1
	v_pk_fma_f32 v[12:13], v[96:97], v[74:75], v[140:141] op_sel_hi:[1,0,1] neg_lo:[0,1,0] neg_hi:[0,1,0]
	v_pk_fma_f32 v[14:15], v[98:99], v[74:75], v[142:143] op_sel_hi:[1,0,1] neg_lo:[0,1,0] neg_hi:[0,1,0]
	v_pk_mul_f32 v[20:21], v[12:13], v[24:25]
	v_pk_mul_f32 v[22:23], v[14:15], v[26:27]
	v_add_f32_dpp v176, v160, v160 row_mirror row_mask:0xf bank_mask:0x3
	s_nop 1
	v_add_f32_dpp v176, v168, v168 row_mirror row_mask:0xf bank_mask:0xc
	s_waitcnt lgkmcnt(4)
	v_pk_mul_f32 v[72:73], v[20:21], v[108:109]
	v_pk_fma_f32 v[72:73], v[22:23], v[110:111], v[72:73]
	v_pk_fma_f32 v[140:141], v[138:139], v[116:117], v[20:21] op_sel_hi:[0,1,1]
	v_add_f32_e32 v74, v72, v73
	v_pk_fma_f32 v[142:143], v[138:139], v[118:119], v[22:23] op_sel_hi:[0,1,1]
	v_pk_mul_f32 v[198:199], v[12:13], v[104:105]
	v_add_f32_dpp v74, v74, v74 quad_perm:[1,0,3,2] row_mask:0xf bank_mask:0xf bound_ctrl:1
	v_pk_fma_f32 v[198:199], v[14:15], v[106:107], v[198:199]
	v_add_f32_e32 v169, v198, v199
	v_add_f32_dpp v74, v74, v74 quad_perm:[2,3,0,1] row_mask:0xf bank_mask:0xf bound_ctrl:1
	ds_read_b128 v[92:95], v70 offset:15360
	ds_read_b128 v[100:103], v70 offset:31744
	v_add_f32_dpp v74, v74, v74 row_half_mirror row_mask:0xf bank_mask:0xf bound_ctrl:1
	ds_read_b128 v[96:99], v70 offset:23552
	ds_read_b128 v[104:107], v70 offset:39936
	v_add_f32_dpp v74, v74, v74 row_mirror row_mask:0xf bank_mask:0xf bound_ctrl:1
	v_pk_fma_f32 v[20:21], v[112:113], v[74:75], v[140:141] op_sel_hi:[1,0,1] neg_lo:[0,1,0] neg_hi:[0,1,0]
	v_pk_fma_f32 v[22:23], v[114:115], v[74:75], v[142:143] op_sel_hi:[1,0,1] neg_lo:[0,1,0] neg_hi:[0,1,0]
	ds_read_b128 v[24:27], v70 offset:7168
	ds_read2_b32 v[136:137], v2 offset0:192 offset1:208
	v_add_f32_dpp v177, v161, v161 row_mirror row_mask:0xf bank_mask:0x3
	s_nop 1
	v_add_f32_dpp v177, v169, v169 row_mirror row_mask:0xf bank_mask:0xc
	s_waitcnt lgkmcnt(6)
; #define RW_LD(X, s) do { X.d = *(const LAS f32x4*)(bs + (s) * 256); X.k = *(const LAS f32x4*)(bs + 8192 + (s) * 256); X.a = *(const LAS f32x4*)(bs + 16384 + (s) * 256); \
;                          X.p = *(const LAS f32x4*)(bs + 24576 + (s) * 256); X.r = *(const LAS f32x4*)(bs + 32768 + (s) * 256); X.v = *(const LAS float*)(bv + (s) * 64); } while (0)
; #define RW_STEP(X, s) do { float sa = fmaf(S[3], X.k[3], fmaf(S[2], X.k[2], fmaf(S[1], X.k[1], S[0] * X.k[0]))); const f32x4 T = S * X.d + X.v * X.p; sa = -red16(sa); \
;                            S = T + sa * X.a; float y = fmaf(S[3], X.r[3], fmaf(S[2], X.r[2], fmaf(S[1], X.r[1], S[0] * X.r[0]))); y = red16(y); \
;                            yk = fmaf(selv[(s) & 15], y, yk); } while (0)
; #define RW_YST(s) do { if ((s) == 15) { ob[(size_t)(rowbase + c * 32 + seg) * D + 512 + h * 64 + vrow] = f2bf(yk); yk = 0.f; } } while (0)
; __device__ __forceinline__ void rwkv_scan(const Params& p, LAS unsigned char* lds, int rowbase, int T, int h, int q4, const float* S0, float* Sout) {
;     ...
;             RwStep xa, xb, xc; float yk = 0.f;
;     ...
;             RW_LD(xa, 0); RW_LD(xb, 1);
; #pragma unroll
;             for (int s = 0; s < 30; s += 3) {
;                 RW_LD(xc, s + 2); RW_STEP(xa, s); RW_YST(s);
;                 RW_LD(xa, s + 3); RW_STEP(xb, s + 1); RW_YST(s + 1);
;                 RW_LD(xb, s + 4); RW_STEP(xc, s + 2); RW_YST(s + 2);
;             }
	v_pk_mul_f32 v[72:73], v[20:21], v[76:77]
	v_pk_fma_f32 v[72:73], v[22:23], v[78:79], v[72:73]
	v_pk_fma_f32 v[140:141], v[138:139], v[84:85], v[20:21] op_sel:[1,0,0] op_sel_hi:[1,1,1]
	v_add_f32_e32 v74, v72, v73
	v_pk_fma_f32 v[142:143], v[138:139], v[86:87], v[22:23] op_sel:[1,0,0] op_sel_hi:[1,1,1]
	v_pk_mul_f32 v[198:199], v[20:21], v[120:121]
	v_add_f32_dpp v74, v74, v74 quad_perm:[1,0,3,2] row_mask:0xf bank_mask:0xf bound_ctrl:1
	v_pk_fma_f32 v[198:199], v[22:23], v[122:123], v[198:199]
	v_add_f32_e32 v170, v198, v199
	v_add_f32_dpp v74, v74, v74 quad_perm:[2,3,0,1] row_mask:0xf bank_mask:0xf bound_ctrl:1
	ds_read_b128 v[108:111], v70 offset:15616
	ds_read_b128 v[116:119], v70 offset:32000
	v_add_f32_dpp v74, v74, v74 row_half_mirror row_mask:0xf bank_mask:0xf bound_ctrl:1
	ds_read_b128 v[112:115], v70 offset:23808
	ds_read_b128 v[120:123], v70 offset:40192
	v_add_f32_dpp v74, v74, v74 row_mirror row_mask:0xf bank_mask:0xf bound_ctrl:1
	v_pk_fma_f32 v[20:21], v[80:81], v[74:75], v[140:141] op_sel_hi:[1,0,1] neg_lo:[0,1,0] neg_hi:[0,1,0]
	v_pk_fma_f32 v[22:23], v[82:83], v[74:75], v[142:143] op_sel_hi:[1,0,1] neg_lo:[0,1,0] neg_hi:[0,1,0]
	v_pk_mul_f32 v[12:13], v[20:21], v[28:29]
	v_pk_mul_f32 v[14:15], v[22:23], v[30:31]
	v_add_f32_dpp v178, v162, v162 row_mirror row_mask:0xf bank_mask:0x3
	s_nop 1
	v_add_f32_dpp v178, v170, v170 row_mirror row_mask:0xf bank_mask:0xc
	s_waitcnt lgkmcnt(4)
	v_pk_mul_f32 v[72:73], v[12:13], v[92:93]
	v_pk_fma_f32 v[72:73], v[14:15], v[94:95], v[72:73]
	v_pk_fma_f32 v[140:141], v[136:137], v[100:101], v[12:13] op_sel_hi:[0,1,1]
	v_add_f32_e32 v74, v72, v73
	v_pk_fma_f32 v[142:143], v[136:137], v[102:103], v[14:15] op_sel_hi:[0,1,1]
	v_pk_mul_f32 v[198:199], v[20:21], v[88:89]
	v_add_f32_dpp v74, v74, v74 quad_perm:[1,0,3,2] row_mask:0xf bank_mask:0xf bound_ctrl:1
	v_pk_fma_f32 v[198:199], v[22:23], v[90:91], v[198:199]
	v_add_f32_e32 v171, v198, v199
	v_add_f32_dpp v74, v74, v74 quad_perm:[2,3,0,1] row_mask:0xf bank_mask:0xf bound_ctrl:1
	ds_read_b128 v[76:79], v70 offset:15872
	ds_read_b128 v[84:87], v70 offset:32256
	v_add_f32_dpp v74, v74, v74 row_half_mirror row_mask:0xf bank_mask:0xf bound_ctrl:1
	ds_read_b128 v[80:83], v70 offset:24064
	ds_read_b128 v[88:91], v70 offset:40448
	v_add_f32_dpp v74, v74, v74 row_mirror row_mask:0xf bank_mask:0xf bound_ctrl:1
	v_pk_fma_f32 v[12:13], v[96:97], v[74:75], v[140:141] op_sel_hi:[1,0,1] neg_lo:[0,1,0] neg_hi:[0,1,0]
	v_pk_fma_f32 v[14:15], v[98:99], v[74:75], v[142:143] op_sel_hi:[1,0,1] neg_lo:[0,1,0] neg_hi:[0,1,0]
	ds_read_b128 v[28:31], v70 offset:7680
	ds_read2_b32 v[138:139], v2 offset0:224 offset1:240
	v_add_f32_dpp v179, v163, v163 row_mirror row_mask:0xf bank_mask:0x3
	s_nop 1
	v_add_f32_dpp v179, v171, v171 row_mirror row_mask:0xf bank_mask:0xc
	s_waitcnt lgkmcnt(6)
	v_pk_mul_f32 v[72:73], v[12:13], v[108:109]
	v_pk_fma_f32 v[72:73], v[14:15], v[110:111], v[72:73]
	v_pk_fma_f32 v[140:141], v[136:137], v[116:117], v[12:13] op_sel:[1,0,0] op_sel_hi:[1,1,1]
	v_add_f32_e32 v74, v72, v73
	v_pk_fma_f32 v[142:143], v[136:137], v[118:119], v[14:15] op_sel:[1,0,0] op_sel_hi:[1,1,1]
	v_pk_mul_f32 v[198:199], v[12:13], v[104:105]
	v_add_f32_dpp v74, v74, v74 quad_perm:[1,0,3,2] row_mask:0xf bank_mask:0xf bound_ctrl:1
	v_pk_fma_f32 v[198:199], v[14:15], v[106:107], v[198:199]
	v_add_f32_e32 v172, v198, v199
	v_add_f32_dpp v74, v74, v74 quad_perm:[2,3,0,1] row_mask:0xf bank_mask:0xf bound_ctrl:1
	ds_read_b128 v[92:95], v70 offset:16128
	ds_read_b128 v[100:103], v70 offset:32512
	v_add_f32_dpp v74, v74, v74 row_half_mirror row_mask:0xf bank_mask:0xf bound_ctrl:1
	ds_read_b128 v[96:99], v70 offset:24320
	ds_read_b128 v[104:107], v70 offset:40704
	v_add_f32_dpp v74, v74, v74 row_mirror row_mask:0xf bank_mask:0xf bound_ctrl:1
	v_pk_fma_f32 v[12:13], v[112:113], v[74:75], v[140:141] op_sel_hi:[1,0,1] neg_lo:[0,1,0] neg_hi:[0,1,0]
	v_pk_fma_f32 v[14:15], v[114:115], v[74:75], v[142:143] op_sel_hi:[1,0,1] neg_lo:[0,1,0] neg_hi:[0,1,0]
	v_pk_mul_f32 v[20:21], v[12:13], v[24:25]
	v_pk_mul_f32 v[22:23], v[14:15], v[26:27]
	v_add_f32_dpp v180, v164, v164 row_mirror row_mask:0xf bank_mask:0x3
	s_nop 1
	v_add_f32_dpp v180, v172, v172 row_mirror row_mask:0xf bank_mask:0xc
	s_waitcnt lgkmcnt(4)
; __device__ __forceinline__ bf16_t f2bf(float f) { return (bf16_t)(cvt_pk_bf16(f, 0.f) & 0xffffu); }
; #define RW_LD(X, s) do { X.d = *(const LAS f32x4*)(bs + (s) * 256); X.k = *(const LAS f32x4*)(bs + 8192 + (s) * 256); X.a = *(const LAS f32x4*)(bs + 16384 + (s) * 256); \
;                          X.p = *(const LAS f32x4*)(bs + 24576 + (s) * 256); X.r = *(const LAS f32x4*)(bs + 32768 + (s) * 256); X.v = *(const LAS float*)(bv + (s) * 64); } while (0)
; #define RW_STEP(X, s) do { float sa = fmaf(S[3], X.k[3], fmaf(S[2], X.k[2], fmaf(S[1], X.k[1], S[0] * X.k[0]))); const f32x4 T = S * X.d + X.v * X.p; sa = -red16(sa); \
;                            S = T + sa * X.a; float y = fmaf(S[3], X.r[3], fmaf(S[2], X.r[2], fmaf(S[1], X.r[1], S[0] * X.r[0]))); y = red16(y); \
;                            yk = fmaf(selv[(s) & 15], y, yk); } while (0)
; #define RW_YST(s) do { if ((s) == 15) { ob[(size_t)(rowbase + c * 32 + seg) * D + 512 + h * 64 + vrow] = f2bf(yk); yk = 0.f; } } while (0)
; __device__ __forceinline__ void rwkv_scan(const Params& p, LAS unsigned char* lds, int rowbase, int T, int h, int q4, const float* S0, float* Sout) {
;     ...
;             for (int s = 0; s < 30; s += 3) {
;                 RW_LD(xc, s + 2); RW_STEP(xa, s); RW_YST(s);
;                 RW_LD(xa, s + 3); RW_STEP(xb, s + 1); RW_YST(s + 1);
;                 RW_LD(xb, s + 4); RW_STEP(xc, s + 2); RW_YST(s + 2);
;             }
;             RW_STEP(xa, 30); RW_STEP(xb, 31);
;             ob[(size_t)(rowbase + c * 32 + 16 + seg) * D + 512 + h * 64 + vrow] = f2bf(yk);
	v_pk_mul_f32 v[72:73], v[20:21], v[76:77]
	v_pk_fma_f32 v[72:73], v[22:23], v[78:79], v[72:73]
	v_pk_fma_f32 v[140:141], v[138:139], v[84:85], v[20:21] op_sel_hi:[0,1,1]
	v_add_f32_e32 v74, v72, v73
	v_pk_fma_f32 v[142:143], v[138:139], v[86:87], v[22:23] op_sel_hi:[0,1,1]
	v_pk_mul_f32 v[198:199], v[12:13], v[120:121]
	v_add_f32_dpp v74, v74, v74 quad_perm:[1,0,3,2] row_mask:0xf bank_mask:0xf bound_ctrl:1
	v_pk_fma_f32 v[198:199], v[14:15], v[122:123], v[198:199]
	v_add_f32_e32 v173, v198, v199
	v_add_f32_dpp v74, v74, v74 quad_perm:[2,3,0,1] row_mask:0xf bank_mask:0xf bound_ctrl:1
	v_add_f32_dpp v184, v176, v176 row_half_mirror row_mask:0xf bank_mask:0x5
	s_nop 1
	v_add_f32_dpp v184, v180, v180 row_half_mirror row_mask:0xf bank_mask:0xa
	v_add_f32_dpp v74, v74, v74 row_half_mirror row_mask:0xf bank_mask:0xf bound_ctrl:1
	s_nop 1
	v_add_f32_dpp v74, v74, v74 row_mirror row_mask:0xf bank_mask:0xf bound_ctrl:1
	v_pk_fma_f32 v[20:21], v[80:81], v[74:75], v[140:141] op_sel_hi:[1,0,1] neg_lo:[0,1,0] neg_hi:[0,1,0]
	v_pk_fma_f32 v[22:23], v[82:83], v[74:75], v[142:143] op_sel_hi:[1,0,1] neg_lo:[0,1,0] neg_hi:[0,1,0]
	s_waitcnt lgkmcnt(0)
	v_pk_mul_f32 v[72:73], v[20:21], v[92:93]
	v_pk_fma_f32 v[72:73], v[22:23], v[94:95], v[72:73]
	v_pk_fma_f32 v[140:141], v[138:139], v[100:101], v[20:21] op_sel:[1,0,0] op_sel_hi:[1,1,1]
	v_add_f32_e32 v74, v72, v73
	v_pk_fma_f32 v[142:143], v[138:139], v[102:103], v[22:23] op_sel:[1,0,0] op_sel_hi:[1,1,1]
	v_pk_mul_f32 v[198:199], v[20:21], v[88:89]
	v_add_f32_dpp v74, v74, v74 quad_perm:[1,0,3,2] row_mask:0xf bank_mask:0xf bound_ctrl:1
	v_pk_fma_f32 v[198:199], v[22:23], v[90:91], v[198:199]
	v_add_f32_e32 v174, v198, v199
	v_add_f32_dpp v74, v74, v74 quad_perm:[2,3,0,1] row_mask:0xf bank_mask:0xf bound_ctrl:1
	v_add_f32_dpp v181, v165, v165 row_mirror row_mask:0xf bank_mask:0x3
	s_nop 1
	v_add_f32_dpp v181, v173, v173 row_mirror row_mask:0xf bank_mask:0xc
	v_add_f32_dpp v74, v74, v74 row_half_mirror row_mask:0xf bank_mask:0xf bound_ctrl:1
	v_add_f32_dpp v185, v177, v177 row_half_mirror row_mask:0xf bank_mask:0x5
	s_nop 0
	v_add_f32_dpp v74, v74, v74 row_mirror row_mask:0xf bank_mask:0xf bound_ctrl:1
	v_pk_fma_f32 v[20:21], v[96:97], v[74:75], v[140:141] op_sel_hi:[1,0,1] neg_lo:[0,1,0] neg_hi:[0,1,0]
	v_pk_fma_f32 v[22:23], v[98:99], v[74:75], v[142:143] op_sel_hi:[1,0,1] neg_lo:[0,1,0] neg_hi:[0,1,0]
	v_pk_mul_f32 v[12:13], v[20:21], v[28:29]
	v_pk_mul_f32 v[14:15], v[22:23], v[30:31]
	v_pk_mul_f32 v[198:199], v[20:21], v[104:105]
	v_pk_fma_f32 v[198:199], v[22:23], v[106:107], v[198:199]
	v_add_f32_e32 v175, v198, v199
	v_add_f32_dpp v185, v181, v181 row_half_mirror row_mask:0xf bank_mask:0xa
	v_add_f32_dpp v182, v166, v166 row_mirror row_mask:0xf bank_mask:0x3
	s_nop 1
	v_add_f32_dpp v182, v174, v174 row_mirror row_mask:0xf bank_mask:0xc
	v_add_f32_dpp v186, v178, v178 row_half_mirror row_mask:0xf bank_mask:0x5
	s_nop 1
	v_add_f32_dpp v186, v182, v182 row_half_mirror row_mask:0xf bank_mask:0xa
	v_cndmask_b32_e64 v190, v184, v186, s[98:99]
	v_cndmask_b32_e64 v191, v186, v184, s[98:99]
	s_nop 1
	v_add_f32_dpp v188, v191, v190 quad_perm:[2,3,0,1] row_mask:0xf bank_mask:0xf
	v_add_f32_dpp v183, v167, v167 row_mirror row_mask:0xf bank_mask:0x3
	s_nop 1
	v_add_f32_dpp v183, v175, v175 row_mirror row_mask:0xf bank_mask:0xc
	v_add_f32_dpp v187, v179, v179 row_half_mirror row_mask:0xf bank_mask:0x5
	s_nop 1
	v_add_f32_dpp v187, v183, v183 row_half_mirror row_mask:0xf bank_mask:0xa
	v_cndmask_b32_e64 v190, v185, v187, s[98:99]
	v_cndmask_b32_e64 v191, v187, v185, s[98:99]
	s_nop 1
	v_add_f32_dpp v189, v191, v190 quad_perm:[2,3,0,1] row_mask:0xf bank_mask:0xf
	v_cndmask_b32_e64 v190, v188, v189, s[100:101]
	v_cndmask_b32_e64 v191, v189, v188, s[100:101]
	s_nop 1
	v_add_f32_dpp v192, v191, v190 quad_perm:[1,0,3,2] row_mask:0xf bank_mask:0xf
	v_add_u32_e32 v196, 16, v196
	v_lshlrev_b32_e32 v194, 11, v196
	v_mov_b32_e32 v195, 0
	v_cvt_pk_bf16_f32 v193, v192, v192
	v_lshl_add_u64 v[194:195], v[42:43], 0, v[194:195]
	global_store_short v[194:195], v193, off offset:1024
	s_branch .LBB0_762
